# c8 + hand-written rg_fused gate math (v_perm+DPP paired bf16 stores, SGPR-base addressing, d16_hi LDS reads, no canonicalise): 1877 vs 2564 instr per direction body
# speedup vs baseline: 1.0031x; 1.0013x over previous
; #define LAS __attribute__((address_space(3)))
; #define RG_WLD(q, ksv) do { _Pragma("unroll") for (int n = 0; n < 4; ++n) \
;                 asm volatile("global_load_dwordx4 %0, %1, %2 offset:%3" : "=&v"(wq[q][n]) : "v"(wvo), "s"(wb[n]), "n"((ksv) * 1024 - 4096) : "memory"); } while (0)
; #define RG_WWAIT(q, cnt) asm volatile("s_waitcnt vmcnt(" #cnt ")" : "+v"(wq[q][0]), "+v"(wq[q][1]), "+v"(wq[q][2]), "+v"(wq[q][3]) :: "memory")
; __device__ __forceinline__ void p_rg_fused(const Frame& F0, const bf16* URAW, int L, const float* cw, const float* cbias, const bf16* Wg, const float* ba, const float* bx, const float* spt,
;                                            bf16* LA, bf16* INP, float* HEND, float* PROD) {
;     ...
;             const int g = Lq >> 4, l15 = Lq & 15, w8 = F.wave;
;             bf16x8 wq[3][4];
;             const unsigned wvo = (unsigned)Lq * 16u;
;             const bf16* wtile0 = Wg + (size_t)((d * 8 + nb) * 2 + (w8 >> 2)) * 65536;
;             const bf16* wb[4];
; #pragma unroll
;             for (int n = 0; n < 4; ++n) wb[n] = wtile0 + (((w8 & 3) * 2 + (n & 1) + (n >> 1) * 8) * 8) * 512 + 2048;
;     ...
;             RG_WLD(0, 0); RG_WLD(1, 1);
;             f32x4 acc[8][4];
;             {
;                 float bn[4];
; #pragma unroll
;                 for (int n = 0; n < 4; ++n) { const int c = nb * 256 + 32 * w8 + 16 * (n & 1) + l15; bn[n] = -1.4426950408889634f * ((n >> 1) ? bx[d * D + c] : ba[d * D + c]); }
; #pragma unroll
;                 for (int m = 0; m < 8; ++m)
; #pragma unroll
;                     for (int n = 0; n < 4; ++n) acc[m][n] = (f32x4){bn[n], bn[n], bn[n], bn[n]};
; #pragma unroll
;                 for (int n = 0; n < 4; ++n) asm volatile("" : "+v"(acc[0][n]));
;             }
; #pragma unroll
;             for (int ks = 0; ks < 8; ++ks) {
;                 if (ks + 2 < 8) RG_WLD((ks + 2) % 3, ks + 2);
;                 if (ks <= 5) RG_WWAIT(ks % 3, 8); else if (ks == 6) RG_WWAIT(ks % 3, 4); else RG_WWAIT(ks % 3, 0);
; #pragma unroll
;                 for (int m = 0; m < 8; ++m) { const bf16x8 a = *(const LAS bf16x8*)(ut + (16 * m + l15) * RGF_PITCH + (32 * ks + 8 * g) * 2);
; #pragma unroll
;                     for (int n = 0; n < 4; ++n) acc[m][n] = __builtin_amdgcn_mfma_f32_16x16x32_bf16(a, wq[ks % 3][n], acc[m][n], 0, 0, 0); }
;                 __builtin_amdgcn_sched_barrier(0);
.LBB0_856:
	s_lshl_b32 s0, s10, 4
	s_add_i32 s0, s2, s0
	s_ashr_i32 s1, s0, 31
	s_xor_b64 s[28:29], s[30:31], -1
	s_lshl_b64 s[0:1], s[0:1], 17
	s_add_u32 s0, s54, s0
	s_addc_u32 s1, s55, s1
	s_add_u32 s16, s0, 0x1000
	s_addc_u32 s17, s1, 0
	s_add_u32 s18, s0, 0x3000
	s_addc_u32 s19, s1, 0
	s_add_u32 s20, s0, 0x11000
	v_mov_b32_e32 v168, v1
	s_addc_u32 s21, s1, 0
	s_add_u32 s22, s0, 0x13000
	v_lshlrev_b32_e32 v50, 4, v168
	global_load_dwordx4 v[2:5], v50, s[16:17] offset:0xfffffffffffff000
	s_addc_u32 s23, s1, 0
	global_load_dwordx4 v[6:9], v50, s[18:19] offset:0xfffffffffffff000
	s_lshl_b32 s38, s10, 11
	global_load_dwordx4 v[10:13], v50, s[20:21] offset:0xfffffffffffff000
	v_and_b32_e32 v144, 15, v168
	s_add_i32 s0, s38, s60
	global_load_dwordx4 v[14:17], v50, s[22:23] offset:0xfffffffffffff000
	v_or_b32_e32 v34, s0, v144
	s_add_i32 s0, s38, s73
	global_load_dwordx4 v[18:21], v50, s[16:17] offset:0xfffffffffffff400
	v_or_b32_e32 v38, s0, v144
	global_load_dwordx4 v[22:25], v50, s[18:19] offset:0xfffffffffffff400
	v_ashrrev_i32_e32 v35, 31, v34
	v_ashrrev_i32_e32 v39, 31, v38
	global_load_dwordx4 v[26:29], v50, s[20:21] offset:0xfffffffffffff400
	v_lshlrev_b64 v[34:35], 2, v[34:35]
	v_lshlrev_b64 v[38:39], 2, v[38:39]
	global_load_dwordx4 v[30:33], v50, s[22:23] offset:0xfffffffffffff400
	v_lshl_add_u64 v[36:37], s[48:49], 0, v[34:35]
	v_lshl_add_u64 v[40:41], s[48:49], 0, v[38:39]
	v_lshl_add_u64 v[34:35], s[50:51], 0, v[34:35]
	global_load_dword v42, v[36:37], off
	s_nop 0
	global_load_dword v40, v[40:41], off
	v_lshl_add_u64 v[36:37], s[50:51], 0, v[38:39]
	global_load_dword v34, v[34:35], off
	s_nop 0
	global_load_dword v35, v[36:37], off
	v_and_b32_e32 v36, -16, v168
	v_mul_u32_u24_e32 v37, 0x210, v144
	v_add3_u32 v70, 0, v36, v37
	s_waitcnt vmcnt(3)
	v_mul_f32_e32 v52, 0xbfb8aa3b, v42
	s_waitcnt vmcnt(2)
	v_mul_f32_e32 v56, 0xbfb8aa3b, v40
	s_waitcnt vmcnt(1)
	v_mul_f32_e32 v60, 0xbfb8aa3b, v34
	s_waitcnt vmcnt(0)
	v_mul_f32_e32 v64, 0xbfb8aa3b, v35
	v_mov_b32_e32 v54, v52
	v_mov_b32_e32 v55, v52
	v_mov_b32_e32 v58, v56
	v_mov_b32_e32 v59, v56
	v_mov_b32_e32 v62, v60
	v_mov_b32_e32 v63, v60
	v_mov_b32_e32 v66, v64
	v_mov_b32_e32 v67, v64
	v_mov_b32_e32 v53, v52
	v_mov_b32_e32 v57, v56
	v_mov_b32_e32 v61, v60
	v_mov_b32_e32 v65, v64
	v_mov_b64_e32 v[74:75], v[54:55]
	v_mov_b64_e32 v[78:79], v[58:59]
	v_mov_b64_e32 v[82:83], v[62:63]
	v_mov_b64_e32 v[86:87], v[66:67]
	v_mov_b64_e32 v[72:73], v[52:53]
	v_mov_b64_e32 v[76:77], v[56:57]
	v_mov_b64_e32 v[80:81], v[60:61]
	v_mov_b64_e32 v[84:85], v[64:65]
	global_load_dwordx4 v[34:37], v50, s[16:17] offset:0xfffffffffffff800
	global_load_dwordx4 v[38:41], v50, s[18:19] offset:0xfffffffffffff800
	global_load_dwordx4 v[42:45], v50, s[20:21] offset:0xfffffffffffff800
	global_load_dwordx4 v[46:49], v50, s[22:23] offset:0xfffffffffffff800
	s_waitcnt vmcnt(8)
	ds_read_b128 v[88:91], v70
	ds_read_b128 v[92:95], v70 offset:8448
	ds_read_b128 v[104:107], v70 offset:16896
	ds_read_b128 v[108:111], v70 offset:25344
	ds_read_b128 v[140:143], v70 offset:33792
	ds_read_b128 v[146:149], v70 offset:42240
	ds_read_b128 v[164:167], v70 offset:50688
	ds_read_b128 v[186:189], v70 offset:59136
	s_waitcnt lgkmcnt(7)
	v_mfma_f32_16x16x32_bf16 v[72:75], v[88:91], v[2:5], v[72:75]
	v_mfma_f32_16x16x32_bf16 v[76:79], v[88:91], v[6:9], v[76:79]
	v_mfma_f32_16x16x32_bf16 v[80:83], v[88:91], v[10:13], v[80:83]
	v_mfma_f32_16x16x32_bf16 v[84:87], v[88:91], v[14:17], v[84:87]
	s_waitcnt lgkmcnt(6)
	v_mfma_f32_16x16x32_bf16 v[88:91], v[92:95], v[2:5], v[52:55]
	v_mfma_f32_16x16x32_bf16 v[96:99], v[92:95], v[6:9], v[56:59]
	v_mfma_f32_16x16x32_bf16 v[100:103], v[92:95], v[10:13], v[60:63]
	v_mfma_f32_16x16x32_bf16 v[92:95], v[92:95], v[14:17], v[64:67]
	s_waitcnt lgkmcnt(5)
	v_mfma_f32_16x16x32_bf16 v[112:115], v[104:107], v[2:5], v[52:55]
	v_mfma_f32_16x16x32_bf16 v[116:119], v[104:107], v[6:9], v[56:59]
	v_mfma_f32_16x16x32_bf16 v[120:123], v[104:107], v[10:13], v[60:63]
	v_mfma_f32_16x16x32_bf16 v[104:107], v[104:107], v[14:17], v[64:67]
	s_waitcnt lgkmcnt(4)
	v_mfma_f32_16x16x32_bf16 v[124:127], v[108:111], v[2:5], v[52:55]
	v_mfma_f32_16x16x32_bf16 v[132:135], v[108:111], v[6:9], v[56:59]
	v_mfma_f32_16x16x32_bf16 v[136:139], v[108:111], v[10:13], v[60:63]
	v_mfma_f32_16x16x32_bf16 v[108:111], v[108:111], v[14:17], v[64:67]
	s_waitcnt lgkmcnt(3)
	v_mfma_f32_16x16x32_bf16 v[150:153], v[140:143], v[2:5], v[52:55]
	v_mfma_f32_16x16x32_bf16 v[154:157], v[140:143], v[6:9], v[56:59]
	v_mfma_f32_16x16x32_bf16 v[170:173], v[140:143], v[10:13], v[60:63]
	v_mfma_f32_16x16x32_bf16 v[140:143], v[140:143], v[14:17], v[64:67]
	s_waitcnt lgkmcnt(2)
	v_mfma_f32_16x16x32_bf16 v[174:177], v[146:149], v[2:5], v[52:55]
	v_mfma_f32_16x16x32_bf16 v[178:181], v[146:149], v[6:9], v[56:59]
	v_mfma_f32_16x16x32_bf16 v[182:185], v[146:149], v[10:13], v[60:63]
	v_mfma_f32_16x16x32_bf16 v[146:149], v[146:149], v[14:17], v[64:67]
	s_waitcnt lgkmcnt(1)
	v_mfma_f32_16x16x32_bf16 v[206:209], v[164:167], v[2:5], v[52:55]
	v_mfma_f32_16x16x32_bf16 v[210:213], v[164:167], v[6:9], v[56:59]
	v_mfma_f32_16x16x32_bf16 v[214:217], v[164:167], v[10:13], v[60:63]
	v_mfma_f32_16x16x32_bf16 v[218:221], v[164:167], v[14:17], v[64:67]
	v_ashrrev_i32_e32 v164, 4, v168
	s_waitcnt lgkmcnt(0)
	v_mfma_f32_16x16x32_bf16 v[52:55], v[186:189], v[2:5], v[52:55]
	v_mfma_f32_16x16x32_bf16 v[56:59], v[186:189], v[6:9], v[56:59]
	v_mfma_f32_16x16x32_bf16 v[60:63], v[186:189], v[10:13], v[60:63]
	v_mfma_f32_16x16x32_bf16 v[64:67], v[186:189], v[14:17], v[64:67]
	global_load_dwordx4 v[2:5], v50, s[16:17] offset:0xfffffffffffffc00
	global_load_dwordx4 v[6:9], v50, s[18:19] offset:0xfffffffffffffc00
	global_load_dwordx4 v[10:13], v50, s[20:21] offset:0xfffffffffffffc00
	global_load_dwordx4 v[14:17], v50, s[22:23] offset:0xfffffffffffffc00
	s_waitcnt vmcnt(8)
; #define LAS __attribute__((address_space(3)))
; #define RG_WLD(q, ksv) do { _Pragma("unroll") for (int n = 0; n < 4; ++n) \
;                 asm volatile("global_load_dwordx4 %0, %1, %2 offset:%3" : "=&v"(wq[q][n]) : "v"(wvo), "s"(wb[n]), "n"((ksv) * 1024 - 4096) : "memory"); } while (0)
; #define RG_WWAIT(q, cnt) asm volatile("s_waitcnt vmcnt(" #cnt ")" : "+v"(wq[q][0]), "+v"(wq[q][1]), "+v"(wq[q][2]), "+v"(wq[q][3]) :: "memory")
; __device__ __forceinline__ void p_rg_fused(const Frame& F0, const bf16* URAW, int L, const float* cw, const float* cbias, const bf16* Wg, const float* ba, const float* bx, const float* spt,
;                                            bf16* LA, bf16* INP, float* HEND, float* PROD) {
;     ...
;             for (int ks = 0; ks < 8; ++ks) {
;                 if (ks + 2 < 8) RG_WLD((ks + 2) % 3, ks + 2);
;                 if (ks <= 5) RG_WWAIT(ks % 3, 8); else if (ks == 6) RG_WWAIT(ks % 3, 4); else RG_WWAIT(ks % 3, 0);
; #pragma unroll
;                 for (int m = 0; m < 8; ++m) { const bf16x8 a = *(const LAS bf16x8*)(ut + (16 * m + l15) * RGF_PITCH + (32 * ks + 8 * g) * 2);
; #pragma unroll
;                     for (int n = 0; n < 4; ++n) acc[m][n] = __builtin_amdgcn_mfma_f32_16x16x32_bf16(a, wq[ks % 3][n], acc[m][n], 0, 0, 0); }
;                 __builtin_amdgcn_sched_barrier(0);
	ds_read_b128 v[186:189], v70 offset:64
	s_waitcnt lgkmcnt(0)
	v_mfma_f32_16x16x32_bf16 v[72:75], v[186:189], v[18:21], v[72:75]
	v_mfma_f32_16x16x32_bf16 v[76:79], v[186:189], v[22:25], v[76:79]
	v_mfma_f32_16x16x32_bf16 v[80:83], v[186:189], v[26:29], v[80:83]
	v_mfma_f32_16x16x32_bf16 v[84:87], v[186:189], v[30:33], v[84:87]
	ds_read_b128 v[186:189], v70 offset:8512
	s_waitcnt lgkmcnt(0)
	v_mfma_f32_16x16x32_bf16 v[88:91], v[186:189], v[18:21], v[88:91]
	v_mfma_f32_16x16x32_bf16 v[96:99], v[186:189], v[22:25], v[96:99]
	v_mfma_f32_16x16x32_bf16 v[100:103], v[186:189], v[26:29], v[100:103]
	v_mfma_f32_16x16x32_bf16 v[92:95], v[186:189], v[30:33], v[92:95]
	ds_read_b128 v[186:189], v70 offset:16960
	s_waitcnt lgkmcnt(0)
	v_mfma_f32_16x16x32_bf16 v[112:115], v[186:189], v[18:21], v[112:115]
	v_mfma_f32_16x16x32_bf16 v[116:119], v[186:189], v[22:25], v[116:119]
	v_mfma_f32_16x16x32_bf16 v[120:123], v[186:189], v[26:29], v[120:123]
	v_mfma_f32_16x16x32_bf16 v[104:107], v[186:189], v[30:33], v[104:107]
	ds_read_b128 v[186:189], v70 offset:25408
	s_waitcnt lgkmcnt(0)
	v_mfma_f32_16x16x32_bf16 v[124:127], v[186:189], v[18:21], v[124:127]
	v_mfma_f32_16x16x32_bf16 v[132:135], v[186:189], v[22:25], v[132:135]
	v_mfma_f32_16x16x32_bf16 v[136:139], v[186:189], v[26:29], v[136:139]
	v_mfma_f32_16x16x32_bf16 v[108:111], v[186:189], v[30:33], v[108:111]
	ds_read_b128 v[186:189], v70 offset:33856
	s_waitcnt lgkmcnt(0)
	v_mfma_f32_16x16x32_bf16 v[150:153], v[186:189], v[18:21], v[150:153]
	v_mfma_f32_16x16x32_bf16 v[154:157], v[186:189], v[22:25], v[154:157]
	v_mfma_f32_16x16x32_bf16 v[170:173], v[186:189], v[26:29], v[170:173]
	v_mfma_f32_16x16x32_bf16 v[140:143], v[186:189], v[30:33], v[140:143]
	ds_read_b128 v[186:189], v70 offset:42304
	s_waitcnt lgkmcnt(0)
	v_mfma_f32_16x16x32_bf16 v[174:177], v[186:189], v[18:21], v[174:177]
	v_mfma_f32_16x16x32_bf16 v[178:181], v[186:189], v[22:25], v[178:181]
	v_mfma_f32_16x16x32_bf16 v[182:185], v[186:189], v[26:29], v[182:185]
	v_mfma_f32_16x16x32_bf16 v[146:149], v[186:189], v[30:33], v[146:149]
	ds_read_b128 v[186:189], v70 offset:50752
	s_waitcnt lgkmcnt(0)
	v_mfma_f32_16x16x32_bf16 v[206:209], v[186:189], v[18:21], v[206:209]
	v_mfma_f32_16x16x32_bf16 v[210:213], v[186:189], v[22:25], v[210:213]
	v_mfma_f32_16x16x32_bf16 v[214:217], v[186:189], v[26:29], v[214:217]
	v_mfma_f32_16x16x32_bf16 v[186:189], v[186:189], v[30:33], v[218:221]
	s_nop 2
	ds_read_b128 v[218:221], v70 offset:59200
	s_waitcnt lgkmcnt(0)
	v_mfma_f32_16x16x32_bf16 v[52:55], v[218:221], v[18:21], v[52:55]
	v_mfma_f32_16x16x32_bf16 v[56:59], v[218:221], v[22:25], v[56:59]
	v_mfma_f32_16x16x32_bf16 v[60:63], v[218:221], v[26:29], v[60:63]
	v_mfma_f32_16x16x32_bf16 v[64:67], v[218:221], v[30:33], v[64:67]
	global_load_dwordx4 v[18:21], v50, s[16:17] offset:0
	global_load_dwordx4 v[22:25], v50, s[18:19] offset:0
	global_load_dwordx4 v[26:29], v50, s[20:21] offset:0
	global_load_dwordx4 v[30:33], v50, s[22:23] offset:0
	s_waitcnt vmcnt(8)
	ds_read_b128 v[218:221], v70 offset:128
	s_waitcnt lgkmcnt(0)
	v_mfma_f32_16x16x32_bf16 v[72:75], v[218:221], v[34:37], v[72:75]
	v_mfma_f32_16x16x32_bf16 v[76:79], v[218:221], v[38:41], v[76:79]
	v_mfma_f32_16x16x32_bf16 v[80:83], v[218:221], v[42:45], v[80:83]
	v_mfma_f32_16x16x32_bf16 v[84:87], v[218:221], v[46:49], v[84:87]
	ds_read_b128 v[218:221], v70 offset:8576
	s_waitcnt lgkmcnt(0)
	v_mfma_f32_16x16x32_bf16 v[88:91], v[218:221], v[34:37], v[88:91]
	v_mfma_f32_16x16x32_bf16 v[96:99], v[218:221], v[38:41], v[96:99]
	v_mfma_f32_16x16x32_bf16 v[100:103], v[218:221], v[42:45], v[100:103]
	v_mfma_f32_16x16x32_bf16 v[92:95], v[218:221], v[46:49], v[92:95]
	ds_read_b128 v[218:221], v70 offset:17024
	s_waitcnt lgkmcnt(0)
	v_mfma_f32_16x16x32_bf16 v[112:115], v[218:221], v[34:37], v[112:115]
	v_mfma_f32_16x16x32_bf16 v[116:119], v[218:221], v[38:41], v[116:119]
	v_mfma_f32_16x16x32_bf16 v[120:123], v[218:221], v[42:45], v[120:123]
	v_mfma_f32_16x16x32_bf16 v[104:107], v[218:221], v[46:49], v[104:107]
	ds_read_b128 v[218:221], v70 offset:25472
	s_waitcnt lgkmcnt(0)
	v_mfma_f32_16x16x32_bf16 v[124:127], v[218:221], v[34:37], v[124:127]
	v_mfma_f32_16x16x32_bf16 v[132:135], v[218:221], v[38:41], v[132:135]
	v_mfma_f32_16x16x32_bf16 v[136:139], v[218:221], v[42:45], v[136:139]
	v_mfma_f32_16x16x32_bf16 v[108:111], v[218:221], v[46:49], v[108:111]
	ds_read_b128 v[218:221], v70 offset:33920
	s_waitcnt lgkmcnt(0)
	v_mfma_f32_16x16x32_bf16 v[150:153], v[218:221], v[34:37], v[150:153]
	v_mfma_f32_16x16x32_bf16 v[154:157], v[218:221], v[38:41], v[154:157]
	v_mfma_f32_16x16x32_bf16 v[170:173], v[218:221], v[42:45], v[170:173]
	v_mfma_f32_16x16x32_bf16 v[140:143], v[218:221], v[46:49], v[140:143]
	ds_read_b128 v[218:221], v70 offset:42368
	s_waitcnt lgkmcnt(0)
	v_mfma_f32_16x16x32_bf16 v[174:177], v[218:221], v[34:37], v[174:177]
	v_mfma_f32_16x16x32_bf16 v[178:181], v[218:221], v[38:41], v[178:181]
	v_mfma_f32_16x16x32_bf16 v[182:185], v[218:221], v[42:45], v[182:185]
	v_mfma_f32_16x16x32_bf16 v[146:149], v[218:221], v[46:49], v[146:149]
	ds_read_b128 v[218:221], v70 offset:50816
	s_waitcnt lgkmcnt(0)
	v_mfma_f32_16x16x32_bf16 v[206:209], v[218:221], v[34:37], v[206:209]
	v_mfma_f32_16x16x32_bf16 v[210:213], v[218:221], v[38:41], v[210:213]
	v_mfma_f32_16x16x32_bf16 v[214:217], v[218:221], v[42:45], v[214:217]
	v_mfma_f32_16x16x32_bf16 v[186:189], v[218:221], v[46:49], v[186:189]
	ds_read_b128 v[218:221], v70 offset:59264
	s_waitcnt lgkmcnt(0)
; #define LAS __attribute__((address_space(3)))
; #define RG_WLD(q, ksv) do { _Pragma("unroll") for (int n = 0; n < 4; ++n) \
;                 asm volatile("global_load_dwordx4 %0, %1, %2 offset:%3" : "=&v"(wq[q][n]) : "v"(wvo), "s"(wb[n]), "n"((ksv) * 1024 - 4096) : "memory"); } while (0)
; #define RG_WWAIT(q, cnt) asm volatile("s_waitcnt vmcnt(" #cnt ")" : "+v"(wq[q][0]), "+v"(wq[q][1]), "+v"(wq[q][2]), "+v"(wq[q][3]) :: "memory")
; __device__ __forceinline__ void p_rg_fused(const Frame& F0, const bf16* URAW, int L, const float* cw, const float* cbias, const bf16* Wg, const float* ba, const float* bx, const float* spt,
;                                            bf16* LA, bf16* INP, float* HEND, float* PROD) {
;     ...
;             for (int ks = 0; ks < 8; ++ks) {
;                 if (ks + 2 < 8) RG_WLD((ks + 2) % 3, ks + 2);
;                 if (ks <= 5) RG_WWAIT(ks % 3, 8); else if (ks == 6) RG_WWAIT(ks % 3, 4); else RG_WWAIT(ks % 3, 0);
; #pragma unroll
;                 for (int m = 0; m < 8; ++m) { const bf16x8 a = *(const LAS bf16x8*)(ut + (16 * m + l15) * RGF_PITCH + (32 * ks + 8 * g) * 2);
; #pragma unroll
;                     for (int n = 0; n < 4; ++n) acc[m][n] = __builtin_amdgcn_mfma_f32_16x16x32_bf16(a, wq[ks % 3][n], acc[m][n], 0, 0, 0); }
;                 __builtin_amdgcn_sched_barrier(0);
	v_mfma_f32_16x16x32_bf16 v[52:55], v[218:221], v[34:37], v[52:55]
	v_mfma_f32_16x16x32_bf16 v[56:59], v[218:221], v[38:41], v[56:59]
	v_mfma_f32_16x16x32_bf16 v[60:63], v[218:221], v[42:45], v[60:63]
	v_mfma_f32_16x16x32_bf16 v[64:67], v[218:221], v[46:49], v[64:67]
	global_load_dwordx4 v[34:37], v50, s[16:17] offset:0x400
	global_load_dwordx4 v[38:41], v50, s[18:19] offset:0x400
	global_load_dwordx4 v[42:45], v50, s[20:21] offset:0x400
	global_load_dwordx4 v[46:49], v50, s[22:23] offset:0x400
	s_waitcnt vmcnt(8)
	ds_read_b128 v[218:221], v70 offset:192
	s_waitcnt lgkmcnt(0)
	v_mfma_f32_16x16x32_bf16 v[72:75], v[218:221], v[2:5], v[72:75]
	v_mfma_f32_16x16x32_bf16 v[76:79], v[218:221], v[6:9], v[76:79]
	v_mfma_f32_16x16x32_bf16 v[80:83], v[218:221], v[10:13], v[80:83]
	v_mfma_f32_16x16x32_bf16 v[84:87], v[218:221], v[14:17], v[84:87]
	ds_read_b128 v[218:221], v70 offset:8640
	s_waitcnt lgkmcnt(0)
	v_mfma_f32_16x16x32_bf16 v[88:91], v[218:221], v[2:5], v[88:91]
	v_mfma_f32_16x16x32_bf16 v[96:99], v[218:221], v[6:9], v[96:99]
	v_mfma_f32_16x16x32_bf16 v[100:103], v[218:221], v[10:13], v[100:103]
	v_mfma_f32_16x16x32_bf16 v[92:95], v[218:221], v[14:17], v[92:95]
	ds_read_b128 v[218:221], v70 offset:17088
	s_waitcnt lgkmcnt(0)
	v_mfma_f32_16x16x32_bf16 v[112:115], v[218:221], v[2:5], v[112:115]
	v_mfma_f32_16x16x32_bf16 v[116:119], v[218:221], v[6:9], v[116:119]
	v_mfma_f32_16x16x32_bf16 v[120:123], v[218:221], v[10:13], v[120:123]
	v_mfma_f32_16x16x32_bf16 v[104:107], v[218:221], v[14:17], v[104:107]
	ds_read_b128 v[218:221], v70 offset:25536
	s_waitcnt lgkmcnt(0)
	v_mfma_f32_16x16x32_bf16 v[124:127], v[218:221], v[2:5], v[124:127]
	v_mfma_f32_16x16x32_bf16 v[132:135], v[218:221], v[6:9], v[132:135]
	v_mfma_f32_16x16x32_bf16 v[136:139], v[218:221], v[10:13], v[136:139]
	v_mfma_f32_16x16x32_bf16 v[108:111], v[218:221], v[14:17], v[108:111]
	ds_read_b128 v[218:221], v70 offset:33984
	s_waitcnt lgkmcnt(0)
	v_mfma_f32_16x16x32_bf16 v[150:153], v[218:221], v[2:5], v[150:153]
	v_mfma_f32_16x16x32_bf16 v[154:157], v[218:221], v[6:9], v[154:157]
	v_mfma_f32_16x16x32_bf16 v[170:173], v[218:221], v[10:13], v[170:173]
	v_mfma_f32_16x16x32_bf16 v[140:143], v[218:221], v[14:17], v[140:143]
	ds_read_b128 v[218:221], v70 offset:42432
	s_waitcnt lgkmcnt(0)
	v_mfma_f32_16x16x32_bf16 v[174:177], v[218:221], v[2:5], v[174:177]
	v_mfma_f32_16x16x32_bf16 v[178:181], v[218:221], v[6:9], v[178:181]
	v_mfma_f32_16x16x32_bf16 v[182:185], v[218:221], v[10:13], v[182:185]
	v_mfma_f32_16x16x32_bf16 v[146:149], v[218:221], v[14:17], v[146:149]
	ds_read_b128 v[218:221], v70 offset:50880
	s_waitcnt lgkmcnt(0)
	v_mfma_f32_16x16x32_bf16 v[206:209], v[218:221], v[2:5], v[206:209]
	v_mfma_f32_16x16x32_bf16 v[210:213], v[218:221], v[6:9], v[210:213]
	v_mfma_f32_16x16x32_bf16 v[214:217], v[218:221], v[10:13], v[214:217]
	v_mfma_f32_16x16x32_bf16 v[186:189], v[218:221], v[14:17], v[186:189]
	ds_read_b128 v[218:221], v70 offset:59328
	s_waitcnt lgkmcnt(0)
	v_mfma_f32_16x16x32_bf16 v[52:55], v[218:221], v[2:5], v[52:55]
	v_mfma_f32_16x16x32_bf16 v[56:59], v[218:221], v[6:9], v[56:59]
	v_mfma_f32_16x16x32_bf16 v[60:63], v[218:221], v[10:13], v[60:63]
	v_mfma_f32_16x16x32_bf16 v[64:67], v[218:221], v[14:17], v[64:67]
	global_load_dwordx4 v[2:5], v50, s[16:17] offset:0x800
	global_load_dwordx4 v[6:9], v50, s[18:19] offset:0x800
	global_load_dwordx4 v[10:13], v50, s[20:21] offset:0x800
	global_load_dwordx4 v[14:17], v50, s[22:23] offset:0x800
	s_waitcnt vmcnt(8)
	ds_read_b128 v[218:221], v70 offset:256
	s_waitcnt lgkmcnt(0)
	v_mfma_f32_16x16x32_bf16 v[72:75], v[218:221], v[18:21], v[72:75]
	v_mfma_f32_16x16x32_bf16 v[76:79], v[218:221], v[22:25], v[76:79]
	v_mfma_f32_16x16x32_bf16 v[80:83], v[218:221], v[26:29], v[80:83]
	v_mfma_f32_16x16x32_bf16 v[84:87], v[218:221], v[30:33], v[84:87]
	ds_read_b128 v[218:221], v70 offset:8704
	s_waitcnt lgkmcnt(0)
	v_mfma_f32_16x16x32_bf16 v[88:91], v[218:221], v[18:21], v[88:91]
	v_mfma_f32_16x16x32_bf16 v[96:99], v[218:221], v[22:25], v[96:99]
	v_mfma_f32_16x16x32_bf16 v[100:103], v[218:221], v[26:29], v[100:103]
	v_mfma_f32_16x16x32_bf16 v[92:95], v[218:221], v[30:33], v[92:95]
	ds_read_b128 v[218:221], v70 offset:17152
	s_waitcnt lgkmcnt(0)
	v_mfma_f32_16x16x32_bf16 v[236:239], v[218:221], v[26:29], v[120:123]
	s_nop 2
	ds_read_b128 v[120:123], v70 offset:25600
	v_mfma_f32_16x16x32_bf16 v[112:115], v[218:221], v[18:21], v[112:115]
	v_mfma_f32_16x16x32_bf16 v[116:119], v[218:221], v[22:25], v[116:119]
	v_mfma_f32_16x16x32_bf16 v[104:107], v[218:221], v[30:33], v[104:107]
	s_waitcnt lgkmcnt(0)
	v_mfma_f32_16x16x32_bf16 v[218:221], v[120:123], v[18:21], v[124:127]
	v_mfma_f32_16x16x32_bf16 v[240:243], v[120:123], v[22:25], v[132:135]
	v_mfma_f32_16x16x32_bf16 v[136:139], v[120:123], v[26:29], v[136:139]
	v_mfma_f32_16x16x32_bf16 v[108:111], v[120:123], v[30:33], v[108:111]
	ds_read_b128 v[120:123], v70 offset:34048
	s_waitcnt lgkmcnt(0)
	v_mfma_f32_16x16x32_bf16 v[150:153], v[120:123], v[18:21], v[150:153]
	v_mfma_f32_16x16x32_bf16 v[154:157], v[120:123], v[22:25], v[154:157]
	v_mfma_f32_16x16x32_bf16 v[170:173], v[120:123], v[26:29], v[170:173]
	v_mfma_f32_16x16x32_bf16 v[140:143], v[120:123], v[30:33], v[140:143]
	ds_read_b128 v[120:123], v70 offset:42496
	s_waitcnt lgkmcnt(0)
	v_mfma_f32_16x16x32_bf16 v[174:177], v[120:123], v[18:21], v[174:177]
	v_mfma_f32_16x16x32_bf16 v[178:181], v[120:123], v[22:25], v[178:181]
	v_mfma_f32_16x16x32_bf16 v[182:185], v[120:123], v[26:29], v[182:185]
	v_mfma_f32_16x16x32_bf16 v[146:149], v[120:123], v[30:33], v[146:149]
	ds_read_b128 v[120:123], v70 offset:50944
	s_waitcnt lgkmcnt(0)
; #define LAS __attribute__((address_space(3)))
; #define RG_WLD(q, ksv) do { _Pragma("unroll") for (int n = 0; n < 4; ++n) \
;                 asm volatile("global_load_dwordx4 %0, %1, %2 offset:%3" : "=&v"(wq[q][n]) : "v"(wvo), "s"(wb[n]), "n"((ksv) * 1024 - 4096) : "memory"); } while (0)
; #define RG_WWAIT(q, cnt) asm volatile("s_waitcnt vmcnt(" #cnt ")" : "+v"(wq[q][0]), "+v"(wq[q][1]), "+v"(wq[q][2]), "+v"(wq[q][3]) :: "memory")
; __device__ __forceinline__ void p_rg_fused(const Frame& F0, const bf16* URAW, int L, const float* cw, const float* cbias, const bf16* Wg, const float* ba, const float* bx, const float* spt,
;                                            bf16* LA, bf16* INP, float* HEND, float* PROD) {
;     ...
;             for (int ks = 0; ks < 8; ++ks) {
;                 if (ks + 2 < 8) RG_WLD((ks + 2) % 3, ks + 2);
;                 if (ks <= 5) RG_WWAIT(ks % 3, 8); else if (ks == 6) RG_WWAIT(ks % 3, 4); else RG_WWAIT(ks % 3, 0);
; #pragma unroll
;                 for (int m = 0; m < 8; ++m) { const bf16x8 a = *(const LAS bf16x8*)(ut + (16 * m + l15) * RGF_PITCH + (32 * ks + 8 * g) * 2);
; #pragma unroll
;                     for (int n = 0; n < 4; ++n) acc[m][n] = __builtin_amdgcn_mfma_f32_16x16x32_bf16(a, wq[ks % 3][n], acc[m][n], 0, 0, 0); }
;                 __builtin_amdgcn_sched_barrier(0);
	v_mfma_f32_16x16x32_bf16 v[206:209], v[120:123], v[18:21], v[206:209]
	v_mfma_f32_16x16x32_bf16 v[210:213], v[120:123], v[22:25], v[210:213]
	v_mfma_f32_16x16x32_bf16 v[214:217], v[120:123], v[26:29], v[214:217]
	v_mfma_f32_16x16x32_bf16 v[186:189], v[120:123], v[30:33], v[186:189]
	ds_read_b128 v[120:123], v70 offset:59392
	s_waitcnt lgkmcnt(0)
	v_mfma_f32_16x16x32_bf16 v[18:21], v[120:123], v[18:21], v[52:55]
	v_mfma_f32_16x16x32_bf16 v[22:25], v[120:123], v[22:25], v[56:59]
	v_mfma_f32_16x16x32_bf16 v[26:29], v[120:123], v[26:29], v[60:63]
	v_mfma_f32_16x16x32_bf16 v[30:33], v[120:123], v[30:33], v[64:67]
	global_load_dwordx4 v[66:69], v50, s[16:17] offset:0xc00
	global_load_dwordx4 v[122:125], v50, s[18:19] offset:0xc00
	global_load_dwordx4 v[126:129], v50, s[20:21] offset:0xc00
	global_load_dwordx4 v[132:135], v50, s[22:23] offset:0xc00
	s_waitcnt vmcnt(8)
	ds_read_b128 v[50:53], v70 offset:320
	s_waitcnt lgkmcnt(0)
	v_mfma_f32_16x16x32_bf16 v[54:57], v[50:53], v[34:37], v[72:75]
	s_nop 2
	ds_read_b128 v[72:75], v70 offset:8768
	v_mfma_f32_16x16x32_bf16 v[58:61], v[50:53], v[38:41], v[76:79]
	v_mfma_f32_16x16x32_bf16 v[62:65], v[50:53], v[42:45], v[80:83]
	s_waitcnt lgkmcnt(0)
	v_mfma_f32_16x16x32_bf16 v[76:79], v[72:75], v[34:37], v[88:91]
	s_nop 2
	ds_read_b128 v[88:91], v70 offset:17216
	v_mfma_f32_16x16x32_bf16 v[50:53], v[50:53], v[46:49], v[84:87]
	v_mfma_f32_16x16x32_bf16 v[80:83], v[72:75], v[38:41], v[96:99]
	v_mfma_f32_16x16x32_bf16 v[84:87], v[72:75], v[42:45], v[100:103]
	v_mfma_f32_16x16x32_bf16 v[72:75], v[72:75], v[46:49], v[92:95]
	s_waitcnt lgkmcnt(0)
	v_mfma_f32_16x16x32_bf16 v[92:95], v[88:91], v[34:37], v[112:115]
	v_mfma_f32_16x16x32_bf16 v[96:99], v[88:91], v[38:41], v[116:119]
	v_mfma_f32_16x16x32_bf16 v[100:103], v[88:91], v[42:45], v[236:239]
	v_mfma_f32_16x16x32_bf16 v[88:91], v[88:91], v[46:49], v[104:107]
	s_nop 2
	ds_read_b128 v[104:107], v70 offset:25664
	s_waitcnt lgkmcnt(0)
	v_mfma_f32_16x16x32_bf16 v[112:115], v[104:107], v[34:37], v[218:221]
	v_mfma_f32_16x16x32_bf16 v[116:119], v[104:107], v[38:41], v[240:243]
	v_mfma_f32_16x16x32_bf16 v[136:139], v[104:107], v[42:45], v[136:139]
	v_mfma_f32_16x16x32_bf16 v[104:107], v[104:107], v[46:49], v[108:111]
	s_nop 2
	ds_read_b128 v[108:111], v70 offset:34112
	s_waitcnt lgkmcnt(0)
	v_mfma_f32_16x16x32_bf16 v[150:153], v[108:111], v[34:37], v[150:153]
	v_mfma_f32_16x16x32_bf16 v[154:157], v[108:111], v[38:41], v[154:157]
	v_mfma_f32_16x16x32_bf16 v[170:173], v[108:111], v[42:45], v[170:173]
	v_mfma_f32_16x16x32_bf16 v[108:111], v[108:111], v[46:49], v[140:143]
	s_nop 2
	ds_read_b128 v[140:143], v70 offset:42560
	s_waitcnt lgkmcnt(0)
	v_mfma_f32_16x16x32_bf16 v[174:177], v[140:143], v[34:37], v[174:177]
	v_mfma_f32_16x16x32_bf16 v[178:181], v[140:143], v[38:41], v[178:181]
	v_mfma_f32_16x16x32_bf16 v[182:185], v[140:143], v[42:45], v[182:185]
	v_mfma_f32_16x16x32_bf16 v[140:143], v[140:143], v[46:49], v[146:149]
	s_nop 2
	ds_read_b128 v[146:149], v70 offset:51008
	s_waitcnt lgkmcnt(0)
	v_mfma_f32_16x16x32_bf16 v[206:209], v[146:149], v[34:37], v[206:209]
	v_mfma_f32_16x16x32_bf16 v[210:213], v[146:149], v[38:41], v[210:213]
	v_mfma_f32_16x16x32_bf16 v[214:217], v[146:149], v[42:45], v[214:217]
	v_mfma_f32_16x16x32_bf16 v[146:149], v[146:149], v[46:49], v[186:189]
	s_nop 2
	ds_read_b128 v[186:189], v70 offset:59456
	s_waitcnt lgkmcnt(0)
	v_mfma_f32_16x16x32_bf16 v[18:21], v[186:189], v[34:37], v[18:21]
	v_mfma_f32_16x16x32_bf16 v[22:25], v[186:189], v[38:41], v[22:25]
	v_mfma_f32_16x16x32_bf16 v[26:29], v[186:189], v[42:45], v[26:29]
	v_mfma_f32_16x16x32_bf16 v[30:33], v[186:189], v[46:49], v[30:33]
	s_waitcnt vmcnt(4)
	ds_read_b128 v[34:37], v70 offset:384
	s_waitcnt lgkmcnt(0)
	v_mfma_f32_16x16x32_bf16 v[38:41], v[34:37], v[2:5], v[54:57]
	v_mfma_f32_16x16x32_bf16 v[42:45], v[34:37], v[6:9], v[58:61]
	v_mfma_f32_16x16x32_bf16 v[46:49], v[34:37], v[10:13], v[62:65]
	s_nop 1
	ds_read_b128 v[58:61], v70 offset:17280
	v_mfma_f32_16x16x32_bf16 v[34:37], v[34:37], v[14:17], v[50:53]
	s_nop 2
	ds_read_b128 v[50:53], v70 offset:8832
	s_waitcnt lgkmcnt(0)
	v_mfma_f32_16x16x32_bf16 v[54:57], v[50:53], v[2:5], v[76:79]
	v_mfma_f32_16x16x32_bf16 v[76:79], v[50:53], v[6:9], v[80:83]
	v_mfma_f32_16x16x32_bf16 v[80:83], v[50:53], v[10:13], v[84:87]
	v_mfma_f32_16x16x32_bf16 v[50:53], v[50:53], v[14:17], v[72:75]
	v_mfma_f32_16x16x32_bf16 v[72:75], v[58:61], v[2:5], v[92:95]
	v_mfma_f32_16x16x32_bf16 v[84:87], v[58:61], v[6:9], v[96:99]
	v_mfma_f32_16x16x32_bf16 v[92:95], v[58:61], v[10:13], v[100:103]
	v_mfma_f32_16x16x32_bf16 v[88:91], v[58:61], v[14:17], v[88:91]
	ds_read_b128 v[58:61], v70 offset:25728
	s_waitcnt lgkmcnt(0)
	v_mfma_f32_16x16x32_bf16 v[96:99], v[58:61], v[2:5], v[112:115]
	v_mfma_f32_16x16x32_bf16 v[186:189], v[58:61], v[6:9], v[116:119]
	v_mfma_f32_16x16x32_bf16 v[218:221], v[58:61], v[10:13], v[136:139]
	v_mfma_f32_16x16x32_bf16 v[236:239], v[58:61], v[14:17], v[104:107]
	ds_read_b128 v[58:61], v70 offset:34176
	s_waitcnt lgkmcnt(0)
	v_mfma_f32_16x16x32_bf16 v[150:153], v[58:61], v[2:5], v[150:153]
	v_mfma_f32_16x16x32_bf16 v[154:157], v[58:61], v[6:9], v[154:157]
	v_mfma_f32_16x16x32_bf16 v[170:173], v[58:61], v[10:13], v[170:173]
	v_mfma_f32_16x16x32_bf16 v[240:243], v[58:61], v[14:17], v[108:111]
	ds_read_b128 v[58:61], v70 offset:42624
	s_waitcnt lgkmcnt(0)
	v_mfma_f32_16x16x32_bf16 v[174:177], v[58:61], v[2:5], v[174:177]
	v_mfma_f32_16x16x32_bf16 v[178:181], v[58:61], v[6:9], v[178:181]
	v_mfma_f32_16x16x32_bf16 v[182:185], v[58:61], v[10:13], v[182:185]
	v_mfma_f32_16x16x32_bf16 v[244:247], v[58:61], v[14:17], v[140:143]
	ds_read_b128 v[58:61], v70 offset:51072
	s_waitcnt lgkmcnt(0)
; __device__ __forceinline__ void p_rg_fused(const Frame& F0, const bf16* URAW, int L, const float* cw, const float* cbias, const bf16* Wg, const float* ba, const float* bx, const float* spt,
;                                            bf16* LA, bf16* INP, float* HEND, float* PROD) {
;     ...
;             for (int ks = 0; ks < 8; ++ks) {
;                 if (ks + 2 < 8) RG_WLD((ks + 2) % 3, ks + 2);
;                 if (ks <= 5) RG_WWAIT(ks % 3, 8); else if (ks == 6) RG_WWAIT(ks % 3, 4); else RG_WWAIT(ks % 3, 0);
; #pragma unroll
;                 for (int m = 0; m < 8; ++m) { const bf16x8 a = *(const LAS bf16x8*)(ut + (16 * m + l15) * RGF_PITCH + (32 * ks + 8 * g) * 2);
; #pragma unroll
;                     for (int n = 0; n < 4; ++n) acc[m][n] = __builtin_amdgcn_mfma_f32_16x16x32_bf16(a, wq[ks % 3][n], acc[m][n], 0, 0, 0); }
;                 __builtin_amdgcn_sched_barrier(0);
;     ...
;             for (int np = 0; np < 2; ++np) {
;                 const int cl = 32 * w8 + 16 * np + l15, c = nb * 256 + cl;
;                 const float psp = spt[d * D + c];
;                 float Lm[8], Hm[8];
; #pragma unroll
;                 for (int m = 0; m < 8; ++m) {
;                     float lr[4], xr[4], ea[4]; unsigned lwv[4], xwv[4];
;                     int gq = g; asm volatile("" : "+v"(gq));
;                     {
;                         f32x4 u4;
; #pragma unroll
;                         for (int e = 0; e < 4; ++e) u4[e] = bf2f(*(const LAS bf16*)(ut + (16 * m + 4 * gq + e) * RGF_PITCH + cl * 2));
;                         const f32x4 na = acc[m][np], nb2 = acc[m][2 + np]; f32x4 e1, e2;
; #pragma unroll
;                         for (int e = 0; e < 4; ++e) { e1[e] = fexp2_(fminf(na[e], 115.f)); e2[e] = fexp2_(fminf(nb2[e], 115.f)); }
;                         const f32x4 d1 = e1 + 1.0f, d2 = e2 + 1.0f, dp = d1 * d2; f32x4 rc;
; #pragma unroll
;                         for (int e = 0; e < 4; ++e) rc[e] = frcp_(dp[e]);
;                         const f32x4 l4 = (d2 * rc) * psp, ig = d1 * rc;
;                         const unsigned lw01 = pk2(l4[0], l4[1]), lw23 = pk2(l4[2], l4[3]);
;                         lr[0] = bflo(lw01); lr[1] = bfhi(lw01); lr[2] = bflo(lw23); lr[3] = bfhi(lw23);
;                         f32x4 ea4, sq;
; #pragma unroll
;                         for (int e = 0; e < 4; ++e) { ea4[e] = fexp2_(lr[e]); ea[e] = ea4[e]; }
; #pragma unroll
	v_mfma_f32_16x16x32_bf16 v[206:209], v[58:61], v[2:5], v[206:209]
	v_mfma_f32_16x16x32_bf16 v[210:213], v[58:61], v[6:9], v[210:213]
	v_mfma_f32_16x16x32_bf16 v[214:217], v[58:61], v[10:13], v[214:217]
	v_mfma_f32_16x16x32_bf16 v[146:149], v[58:61], v[14:17], v[146:149]
	ds_read_b128 v[58:61], v70 offset:59520
	s_waitcnt lgkmcnt(0)
	v_mfma_f32_16x16x32_bf16 v[2:5], v[58:61], v[2:5], v[18:21]
	v_mfma_f32_16x16x32_bf16 v[6:9], v[58:61], v[6:9], v[22:25]
	v_mfma_f32_16x16x32_bf16 v[194:197], v[58:61], v[10:13], v[26:29]
	v_mfma_f32_16x16x32_bf16 v[222:225], v[58:61], v[14:17], v[30:33]
	s_waitcnt vmcnt(0)
	ds_read_b128 v[10:13], v70 offset:448
	s_waitcnt lgkmcnt(0)
	v_mfma_f32_16x16x32_bf16 v[140:143], v[10:13], v[66:69], v[38:41]
	v_mfma_f32_16x16x32_bf16 v[62:65], v[10:13], v[122:125], v[42:45]
	v_mfma_f32_16x16x32_bf16 v[136:139], v[10:13], v[126:129], v[46:49]
	v_mfma_f32_16x16x32_bf16 v[58:61], v[10:13], v[132:135], v[34:37]
	ds_read_b128 v[10:13], v70 offset:8896
	s_waitcnt lgkmcnt(0)
	v_mfma_f32_16x16x32_bf16 v[118:121], v[10:13], v[66:69], v[54:57]
	v_mfma_f32_16x16x32_bf16 v[54:57], v[10:13], v[122:125], v[76:79]
	v_mfma_f32_16x16x32_bf16 v[114:117], v[10:13], v[126:129], v[80:83]
	v_mfma_f32_16x16x32_bf16 v[50:53], v[10:13], v[132:135], v[50:53]
	ds_read_b128 v[10:13], v70 offset:17344
	s_waitcnt lgkmcnt(0)
	v_mfma_f32_16x16x32_bf16 v[110:113], v[10:13], v[66:69], v[72:75]
	v_mfma_f32_16x16x32_bf16 v[46:49], v[10:13], v[122:125], v[84:87]
	v_mfma_f32_16x16x32_bf16 v[106:109], v[10:13], v[126:129], v[92:95]
	v_mfma_f32_16x16x32_bf16 v[42:45], v[10:13], v[132:135], v[88:91]
	ds_read_b128 v[10:13], v70 offset:25792
	s_waitcnt lgkmcnt(0)
	v_mfma_f32_16x16x32_bf16 v[102:105], v[10:13], v[66:69], v[96:99]
	v_mfma_f32_16x16x32_bf16 v[38:41], v[10:13], v[122:125], v[186:189]
	v_mfma_f32_16x16x32_bf16 v[98:101], v[10:13], v[126:129], v[218:221]
	v_mfma_f32_16x16x32_bf16 v[34:37], v[10:13], v[132:135], v[236:239]
	ds_read_b128 v[10:13], v70 offset:34240
	s_waitcnt lgkmcnt(0)
	v_mfma_f32_16x16x32_bf16 v[94:97], v[10:13], v[66:69], v[150:153]
	v_mfma_f32_16x16x32_bf16 v[30:33], v[10:13], v[122:125], v[154:157]
	v_mfma_f32_16x16x32_bf16 v[90:93], v[10:13], v[126:129], v[170:173]
	v_mfma_f32_16x16x32_bf16 v[26:29], v[10:13], v[132:135], v[240:243]
	ds_read_b128 v[10:13], v70 offset:42688
	s_waitcnt lgkmcnt(0)
	v_mfma_f32_16x16x32_bf16 v[86:89], v[10:13], v[66:69], v[174:177]
	v_mfma_f32_16x16x32_bf16 v[22:25], v[10:13], v[122:125], v[178:181]
	v_mfma_f32_16x16x32_bf16 v[82:85], v[10:13], v[126:129], v[182:185]
	v_mfma_f32_16x16x32_bf16 v[18:21], v[10:13], v[132:135], v[244:247]
	ds_read_b128 v[10:13], v70 offset:51136
	s_waitcnt lgkmcnt(0)
	v_mfma_f32_16x16x32_bf16 v[78:81], v[10:13], v[66:69], v[206:209]
	v_mfma_f32_16x16x32_bf16 v[14:17], v[10:13], v[122:125], v[210:213]
	v_mfma_f32_16x16x32_bf16 v[74:77], v[10:13], v[126:129], v[214:217]
	v_mfma_f32_16x16x32_bf16 v[10:13], v[10:13], v[132:135], v[146:149]
	s_nop 2
	ds_read_b128 v[146:149], v70 offset:59584
	s_waitcnt lgkmcnt(0)
	v_mfma_f32_16x16x32_bf16 v[70:73], v[146:149], v[66:69], v[2:5]
	v_mfma_f32_16x16x32_bf16 v[6:9], v[146:149], v[122:125], v[6:9]
	v_mfma_f32_16x16x32_bf16 v[66:69], v[146:149], v[126:129], v[194:197]
	v_mfma_f32_16x16x32_bf16 v[2:5], v[146:149], v[132:135], v[222:225]
	v_or_b32_e32 v122, s35, v144
	v_and_b32_e32 v124, 1, v168
	v_mul_u32_u24_e32 v123, s83, v164
	v_cmp_eq_u32_e64 s[36:37], 0, v124
	v_lshl_add_u32 v123, v122, 1, v123
	v_add_u32_e32 v128, s57, v122
	v_lshlrev_b32_e32 v128, 2, v128
	s_lshl_b32 s0, s10, 13
	s_add_u32 s0, s86, s0
	s_addc_u32 s1, s87, 0
	global_load_dword v132, v128, s[0:1]
	global_load_dword v134, v128, s[0:1] offset:64
	v_mov_b32_e32 v125, 0x3020706
	v_mov_b32_e32 v129, 0x5040100
	v_cndmask_b32_e64 v125, v125, v129, s[36:37]
	v_lshl_or_b32 v126, v164, 2, v124
	v_and_b32_e32 v127, -2, v122
	v_lshlrev_b32_e32 v127, 1, v127
	v_lshl_add_u32 v126, v126, 12, v127
	v_add_u32_e32 v127, 0x2000, v126
	v_lshlrev_b32_e32 v130, 2, v168
	v_xor_b32_e32 v129, 64, v130
	v_xor_b32_e32 v130, 0x80, v130
	v_bfe_u32 v210, v168, 4, 1
	v_bfe_u32 v211, v168, 5, 1
	v_cmp_eq_u32_e64 s[40:41], s10, v210
	v_cmp_eq_u32_e64 s[38:39], s10, v211
	v_cmp_gt_u32_e64 s[42:43], 16, v168
	v_mov_b32_e32 v144, 0
	v_mov_b32_e32 v145, 0
	v_mov_b32_e32 v146, 0
	v_mov_b32_e32 v147, 0
	v_mov_b32_e32 v148, 0
	v_mov_b32_e32 v149, 0
	v_mov_b32_e32 v150, 0
	v_mov_b32_e32 v151, 0
	s_mov_b32 s20, 0x42e60000
	s_mov_b32 s21, 0xffff0000
	s_lshl_b32 s0, s10, 25
	s_add_u32 s16, s61, s0
	s_addc_u32 s17, s71, 0
	s_add_u32 s18, s65, s0
	s_addc_u32 s19, s72, 0
	ds_read_u16_d16_hi v144, v123 offset:0
	ds_read_u16_d16_hi v145, v123 offset:528
	ds_read_u16_d16_hi v146, v123 offset:1056
	ds_read_u16_d16_hi v147, v123 offset:1584
	ds_read_u16_d16_hi v148, v123 offset:8448
	ds_read_u16_d16_hi v149, v123 offset:8976
	ds_read_u16_d16_hi v150, v123 offset:9504
	ds_read_u16_d16_hi v151, v123 offset:10032
	v_min_f32_e32 v140, s20, v140
	v_min_f32_e32 v141, s20, v141
	v_min_f32_e32 v142, s20, v142
	v_min_f32_e32 v143, s20, v143
	v_min_f32_e32 v136, s20, v136
	v_min_f32_e32 v137, s20, v137
	v_min_f32_e32 v138, s20, v138
	v_min_f32_e32 v139, s20, v139
	v_exp_f32_e32 v140, v140
	v_exp_f32_e32 v141, v141
	v_exp_f32_e32 v142, v142
	v_exp_f32_e32 v143, v143
	v_exp_f32_e32 v136, v136
	v_exp_f32_e32 v137, v137
	v_exp_f32_e32 v138, v138
	v_exp_f32_e32 v139, v139
	v_pk_add_f32 v[140:141], v[140:141], 1.0 op_sel_hi:[1,0]
	v_pk_add_f32 v[142:143], v[142:143], 1.0 op_sel_hi:[1,0]
	v_pk_add_f32 v[136:137], v[136:137], 1.0 op_sel_hi:[1,0]
	v_pk_add_f32 v[138:139], v[138:139], 1.0 op_sel_hi:[1,0]
	v_pk_mul_f32 v[178:179], v[140:141], v[136:137]
	v_pk_mul_f32 v[180:181], v[142:143], v[138:139]
	v_rcp_f32_e32 v178, v178
	v_rcp_f32_e32 v179, v179
	v_rcp_f32_e32 v180, v180
	v_rcp_f32_e32 v181, v181
	v_pk_mul_f32 v[136:137], v[136:137], v[178:179]
	v_pk_mul_f32 v[138:139], v[138:139], v[180:181]
	v_pk_mul_f32 v[140:141], v[140:141], v[178:179]
	v_pk_mul_f32 v[142:143], v[142:143], v[180:181]
	s_waitcnt vmcnt(0)
; #define LAS __attribute__((address_space(3)))
; __device__ __forceinline__ void p_rg_fused(const Frame& F0, const bf16* URAW, int L, const float* cw, const float* cbias, const bf16* Wg, const float* ba, const float* bx, const float* spt,
;                                            bf16* LA, bf16* INP, float* HEND, float* PROD) {
;     ...
;                 for (int m = 0; m < 8; ++m) {
;                     float lr[4], xr[4], ea[4]; unsigned lwv[4], xwv[4];
;                     int gq = g; asm volatile("" : "+v"(gq));
;                     {
;                         f32x4 u4;
; #pragma unroll
;                         for (int e = 0; e < 4; ++e) u4[e] = bf2f(*(const LAS bf16*)(ut + (16 * m + 4 * gq + e) * RGF_PITCH + cl * 2));
;                         const f32x4 na = acc[m][np], nb2 = acc[m][2 + np]; f32x4 e1, e2;
; #pragma unroll
;                         for (int e = 0; e < 4; ++e) { e1[e] = fexp2_(fminf(na[e], 115.f)); e2[e] = fexp2_(fminf(nb2[e], 115.f)); }
;                         const f32x4 d1 = e1 + 1.0f, d2 = e2 + 1.0f, dp = d1 * d2; f32x4 rc;
; #pragma unroll
;                         for (int e = 0; e < 4; ++e) rc[e] = frcp_(dp[e]);
;                         const f32x4 l4 = (d2 * rc) * psp, ig = d1 * rc;
;                         const unsigned lw01 = pk2(l4[0], l4[1]), lw23 = pk2(l4[2], l4[3]);
;                         lr[0] = bflo(lw01); lr[1] = bfhi(lw01); lr[2] = bflo(lw23); lr[3] = bfhi(lw23);
;                         f32x4 ea4, sq;
; #pragma unroll
;                         for (int e = 0; e < 4; ++e) { ea4[e] = fexp2_(lr[e]); ea[e] = ea4[e]; }
; #pragma unroll
;                         for (int e = 0; e < 4; ++e) sq[e] = fsqrt_(__builtin_fabsf(__builtin_fmaf(-ea4[e], ea4[e], 1.0f)));
;                         const f32x4 x4 = sq * ig * u4;
;                         const unsigned xw01 = pk2(x4[0], x4[1]), xw23 = pk2(x4[2], x4[3]);
;                         xr[0] = bflo(xw01); xr[1] = bfhi(xw01); xr[2] = bflo(xw23); xr[3] = bfhi(xw23);
;                         lwv[0] = lw01 & 0xffffu; lwv[1] = lw01 >> 16; lwv[2] = lw23 & 0xffffu; lwv[3] = lw23 >> 16;
;                         xwv[0] = xw01 & 0xffffu; xwv[1] = xw01 >> 16; xwv[2] = xw23 & 0xffffu; xwv[3] = xw23 >> 16; }
; #pragma unroll
;                     for (int ep = 0; ep < 2; ++ep) { const bool odd = (Lq & 1) != 0; const int tok = 16 * m + 4 * gq + 2 * ep + (odd ? 1 : 0);
	v_pk_mul_f32 v[136:137], v[136:137], v[132:133] op_sel_hi:[1,0]
	v_pk_mul_f32 v[138:139], v[138:139], v[132:133] op_sel_hi:[1,0]
	v_cvt_pk_bf16_f32 v178, v136, v137
	v_cvt_pk_bf16_f32 v179, v138, v139
	v_lshlrev_b32_e32 v136, 16, v178
	v_lshlrev_b32_e32 v137, 16, v179
	v_and_b32_e32 v138, s21, v178
	v_and_b32_e32 v139, s21, v179
	v_exp_f32_e32 v184, v136
	v_exp_f32_e32 v185, v138
	v_exp_f32_e32 v186, v137
	v_exp_f32_e32 v187, v139
	v_fma_f32 v180, -v184, v184, 1.0
	v_fma_f32 v181, -v185, v185, 1.0
	v_fma_f32 v182, -v186, v186, 1.0
	v_fma_f32 v183, -v187, v187, 1.0
	v_sqrt_f32_e64 v180, |v180|
	v_sqrt_f32_e64 v181, |v181|
	v_sqrt_f32_e64 v182, |v182|
	v_sqrt_f32_e64 v183, |v183|
	v_mov_b32_dpp v188, v178 quad_perm:[1,0,3,2] row_mask:0xf bank_mask:0xf bound_ctrl:1
	v_mov_b32_dpp v165, v179 quad_perm:[1,0,3,2] row_mask:0xf bank_mask:0xf bound_ctrl:1
	v_pk_mul_f32 v[180:181], v[180:181], v[140:141]
	v_pk_mul_f32 v[182:183], v[182:183], v[142:143]
	v_perm_b32 v206, v188, v178, v125
	v_perm_b32 v207, v165, v179, v125
	global_store_dword v126, v206, s[16:17] offset:0
	global_store_dword v127, v207, s[16:17] offset:0
	s_waitcnt lgkmcnt(4)
	v_pk_mul_f32 v[180:181], v[180:181], v[144:145]
	v_pk_mul_f32 v[182:183], v[182:183], v[146:147]
	v_pk_add_f32 v[136:137], v[136:137], v[138:139]
	v_cvt_pk_bf16_f32 v140, v180, v181
	v_cvt_pk_bf16_f32 v141, v182, v183
	v_add_f32_e32 v152, v136, v137
	v_lshlrev_b32_e32 v180, 16, v140
	v_mov_b32_dpp v188, v140 quad_perm:[1,0,3,2] row_mask:0xf bank_mask:0xf bound_ctrl:1
	v_and_b32_e32 v181, s21, v140
	v_mov_b32_dpp v165, v141 quad_perm:[1,0,3,2] row_mask:0xf bank_mask:0xf bound_ctrl:1
	v_lshlrev_b32_e32 v182, 16, v141
	v_and_b32_e32 v183, s21, v141
	v_perm_b32 v208, v188, v140, v125
	v_perm_b32 v209, v165, v141, v125
	global_store_dword v126, v208, s[18:19] offset:0
	global_store_dword v127, v209, s[18:19] offset:0
	s_add_u32 s16, s16, 0x10000
	s_addc_u32 s17, s17, 0
	s_add_u32 s18, s18, 0x10000
	s_addc_u32 s19, s19, 0
	v_fma_f32 v214, v180, v185, v181
	v_fma_f32 v215, v183, v186, v182
	v_fma_f32 v214, v214, v186, v182
	v_fma_f32 v215, v215, v185, v181
	v_fma_f32 v214, v214, v187, v183
	v_fma_f32 v215, v215, v184, v180
	ds_bpermute_b32 v210, v129, v152
	v_cndmask_b32_e64 v169, v215, v214, s[30:31]
	v_exp_f32_e32 v212, v152
	ds_bpermute_b32 v211, v129, v169
	ds_read_u16_d16_hi v144, v123 offset:16896
	ds_read_u16_d16_hi v145, v123 offset:17424
	ds_read_u16_d16_hi v146, v123 offset:17952
	ds_read_u16_d16_hi v147, v123 offset:18480
	v_min_f32_e32 v118, s20, v118
	v_min_f32_e32 v119, s20, v119
	v_min_f32_e32 v120, s20, v120
	v_min_f32_e32 v121, s20, v121
	v_min_f32_e32 v114, s20, v114
	v_min_f32_e32 v115, s20, v115
	v_min_f32_e32 v116, s20, v116
	v_min_f32_e32 v117, s20, v117
	v_exp_f32_e32 v118, v118
	v_exp_f32_e32 v119, v119
	v_exp_f32_e32 v120, v120
	v_exp_f32_e32 v121, v121
	v_exp_f32_e32 v114, v114
	v_exp_f32_e32 v115, v115
	v_exp_f32_e32 v116, v116
	v_exp_f32_e32 v117, v117
	v_pk_add_f32 v[118:119], v[118:119], 1.0 op_sel_hi:[1,0]
	v_pk_add_f32 v[120:121], v[120:121], 1.0 op_sel_hi:[1,0]
	v_pk_add_f32 v[114:115], v[114:115], 1.0 op_sel_hi:[1,0]
	v_pk_add_f32 v[116:117], v[116:117], 1.0 op_sel_hi:[1,0]
	v_pk_mul_f32 v[216:217], v[118:119], v[114:115]
	v_pk_mul_f32 v[218:219], v[120:121], v[116:117]
	v_rcp_f32_e32 v216, v216
	v_rcp_f32_e32 v217, v217
	v_rcp_f32_e32 v218, v218
	v_rcp_f32_e32 v219, v219
	v_pk_mul_f32 v[114:115], v[114:115], v[216:217]
	v_pk_mul_f32 v[116:117], v[116:117], v[218:219]
	v_pk_mul_f32 v[118:119], v[118:119], v[216:217]
	v_pk_mul_f32 v[120:121], v[120:121], v[218:219]
	v_pk_mul_f32 v[114:115], v[114:115], v[132:133] op_sel_hi:[1,0]
	v_pk_mul_f32 v[116:117], v[116:117], v[132:133] op_sel_hi:[1,0]
	v_cvt_pk_bf16_f32 v216, v114, v115
	v_cvt_pk_bf16_f32 v217, v116, v117
	v_lshlrev_b32_e32 v114, 16, v216
	v_lshlrev_b32_e32 v115, 16, v217
	v_and_b32_e32 v116, s21, v216
	v_and_b32_e32 v117, s21, v217
	v_exp_f32_e32 v222, v114
	v_exp_f32_e32 v223, v116
	v_exp_f32_e32 v224, v115
	v_exp_f32_e32 v225, v117
	s_waitcnt lgkmcnt(4)
	v_exp_f32_e32 v213, v210
	v_fma_f32 v215, v211, v212, v169
	v_add_f32_e32 v152, v152, v210
	v_fma_f32 v214, v169, v213, v211
	v_cndmask_b32_e64 v169, v215, v214, s[40:41]
	ds_bpermute_b32 v210, v130, v152
	v_exp_f32_e32 v212, v152
	ds_bpermute_b32 v211, v130, v169
	v_fma_f32 v218, -v222, v222, 1.0
	v_fma_f32 v219, -v223, v223, 1.0
	v_fma_f32 v220, -v224, v224, 1.0
	v_fma_f32 v221, -v225, v225, 1.0
	v_sqrt_f32_e64 v218, |v218|
	v_sqrt_f32_e64 v219, |v219|
	v_sqrt_f32_e64 v220, |v220|
	v_sqrt_f32_e64 v221, |v221|
	v_mov_b32_dpp v166, v216 quad_perm:[1,0,3,2] row_mask:0xf bank_mask:0xf bound_ctrl:1
	v_mov_b32_dpp v167, v217 quad_perm:[1,0,3,2] row_mask:0xf bank_mask:0xf bound_ctrl:1
	v_pk_mul_f32 v[218:219], v[218:219], v[118:119]
	v_pk_mul_f32 v[220:221], v[220:221], v[120:121]
	v_perm_b32 v236, v166, v216, v125
	v_perm_b32 v237, v167, v217, v125
	global_store_dword v126, v236, s[16:17] offset:0
	global_store_dword v127, v237, s[16:17] offset:0
	v_pk_mul_f32 v[218:219], v[218:219], v[148:149]
	v_pk_mul_f32 v[220:221], v[220:221], v[150:151]
	v_pk_add_f32 v[114:115], v[114:115], v[116:117]
	v_cvt_pk_bf16_f32 v118, v218, v219
	v_cvt_pk_bf16_f32 v119, v220, v221
	v_add_f32_e32 v153, v114, v115
	v_lshlrev_b32_e32 v218, 16, v118
	v_mov_b32_dpp v166, v118 quad_perm:[1,0,3,2] row_mask:0xf bank_mask:0xf bound_ctrl:1
	v_and_b32_e32 v219, s21, v118
	v_mov_b32_dpp v167, v119 quad_perm:[1,0,3,2] row_mask:0xf bank_mask:0xf bound_ctrl:1
	v_lshlrev_b32_e32 v220, 16, v119
	v_and_b32_e32 v221, s21, v119
	v_perm_b32 v238, v166, v118, v125
	v_perm_b32 v239, v167, v119, v125
	global_store_dword v126, v238, s[18:19] offset:0
	global_store_dword v127, v239, s[18:19] offset:0
	s_add_u32 s16, s16, 0x10000
	s_addc_u32 s17, s17, 0
	s_add_u32 s18, s18, 0x10000
	s_addc_u32 s19, s19, 0
	v_fma_f32 v244, v218, v223, v219
	v_fma_f32 v245, v221, v224, v220
	v_fma_f32 v244, v244, v224, v220
	v_fma_f32 v245, v245, v223, v219
	v_fma_f32 v244, v244, v225, v221
	v_fma_f32 v245, v245, v222, v218
	ds_bpermute_b32 v240, v129, v153
	v_cndmask_b32_e64 v170, v245, v244, s[30:31]
	v_exp_f32_e32 v242, v153
	ds_bpermute_b32 v241, v129, v170
	s_waitcnt lgkmcnt(2)
; #define LAS __attribute__((address_space(3)))
; __device__ __forceinline__ void p_rg_fused(const Frame& F0, const bf16* URAW, int L, const float* cw, const float* cbias, const bf16* Wg, const float* ba, const float* bx, const float* spt,
;                                            bf16* LA, bf16* INP, float* HEND, float* PROD) {
;     ...
;                 for (int m = 0; m < 8; ++m) {
;                     float lr[4], xr[4], ea[4]; unsigned lwv[4], xwv[4];
;                     int gq = g; asm volatile("" : "+v"(gq));
;                     {
;                         f32x4 u4;
; #pragma unroll
;                         for (int e = 0; e < 4; ++e) u4[e] = bf2f(*(const LAS bf16*)(ut + (16 * m + 4 * gq + e) * RGF_PITCH + cl * 2));
;                         const f32x4 na = acc[m][np], nb2 = acc[m][2 + np]; f32x4 e1, e2;
; #pragma unroll
;                         for (int e = 0; e < 4; ++e) { e1[e] = fexp2_(fminf(na[e], 115.f)); e2[e] = fexp2_(fminf(nb2[e], 115.f)); }
;                         const f32x4 d1 = e1 + 1.0f, d2 = e2 + 1.0f, dp = d1 * d2; f32x4 rc;
; #pragma unroll
;                         for (int e = 0; e < 4; ++e) rc[e] = frcp_(dp[e]);
;                         const f32x4 l4 = (d2 * rc) * psp, ig = d1 * rc;
;                         const unsigned lw01 = pk2(l4[0], l4[1]), lw23 = pk2(l4[2], l4[3]);
;                         lr[0] = bflo(lw01); lr[1] = bfhi(lw01); lr[2] = bflo(lw23); lr[3] = bfhi(lw23);
;                         f32x4 ea4, sq;
; #pragma unroll
;                         for (int e = 0; e < 4; ++e) { ea4[e] = fexp2_(lr[e]); ea[e] = ea4[e]; }
; #pragma unroll
;                         for (int e = 0; e < 4; ++e) sq[e] = fsqrt_(__builtin_fabsf(__builtin_fmaf(-ea4[e], ea4[e], 1.0f)));
;                         const f32x4 x4 = sq * ig * u4;
;                         const unsigned xw01 = pk2(x4[0], x4[1]), xw23 = pk2(x4[2], x4[3]);
;                         xr[0] = bflo(xw01); xr[1] = bfhi(xw01); xr[2] = bflo(xw23); xr[3] = bfhi(xw23);
;                         lwv[0] = lw01 & 0xffffu; lwv[1] = lw01 >> 16; lwv[2] = lw23 & 0xffffu; lwv[3] = lw23 >> 16;
;                         xwv[0] = xw01 & 0xffffu; xwv[1] = xw01 >> 16; xwv[2] = xw23 & 0xffffu; xwv[3] = xw23 >> 16; }
; #pragma unroll
;                     for (int ep = 0; ep < 2; ++ep) { const bool odd = (Lq & 1) != 0; const int tok = 16 * m + 4 * gq + 2 * ep + (odd ? 1 : 0);
	v_exp_f32_e32 v213, v210
	v_fma_f32 v215, v211, v212, v169
	v_add_f32_e32 v152, v152, v210
	v_fma_f32 v214, v169, v213, v211
	v_cndmask_b32_e64 v169, v215, v214, s[38:39]
	ds_read_u16_d16_hi v148, v123 offset:25344
	ds_read_u16_d16_hi v149, v123 offset:25872
	ds_read_u16_d16_hi v150, v123 offset:26400
	ds_read_u16_d16_hi v151, v123 offset:26928
	v_min_f32_e32 v110, s20, v110
	v_min_f32_e32 v111, s20, v111
	v_min_f32_e32 v112, s20, v112
	v_min_f32_e32 v113, s20, v113
	v_min_f32_e32 v106, s20, v106
	v_min_f32_e32 v107, s20, v107
	v_min_f32_e32 v108, s20, v108
	v_min_f32_e32 v109, s20, v109
	v_exp_f32_e32 v110, v110
	v_exp_f32_e32 v111, v111
	v_exp_f32_e32 v112, v112
	v_exp_f32_e32 v113, v113
	v_exp_f32_e32 v106, v106
	v_exp_f32_e32 v107, v107
	v_exp_f32_e32 v108, v108
	v_exp_f32_e32 v109, v109
	v_pk_add_f32 v[110:111], v[110:111], 1.0 op_sel_hi:[1,0]
	v_pk_add_f32 v[112:113], v[112:113], 1.0 op_sel_hi:[1,0]
	v_pk_add_f32 v[106:107], v[106:107], 1.0 op_sel_hi:[1,0]
	v_pk_add_f32 v[108:109], v[108:109], 1.0 op_sel_hi:[1,0]
	v_pk_mul_f32 v[178:179], v[110:111], v[106:107]
	v_pk_mul_f32 v[180:181], v[112:113], v[108:109]
	v_rcp_f32_e32 v178, v178
	v_rcp_f32_e32 v179, v179
	v_rcp_f32_e32 v180, v180
	v_rcp_f32_e32 v181, v181
	v_pk_mul_f32 v[106:107], v[106:107], v[178:179]
	v_pk_mul_f32 v[108:109], v[108:109], v[180:181]
	v_pk_mul_f32 v[110:111], v[110:111], v[178:179]
	v_pk_mul_f32 v[112:113], v[112:113], v[180:181]
	v_pk_mul_f32 v[106:107], v[106:107], v[132:133] op_sel_hi:[1,0]
	v_pk_mul_f32 v[108:109], v[108:109], v[132:133] op_sel_hi:[1,0]
	v_cvt_pk_bf16_f32 v178, v106, v107
	v_cvt_pk_bf16_f32 v179, v108, v109
	v_lshlrev_b32_e32 v106, 16, v178
	v_lshlrev_b32_e32 v107, 16, v179
	v_and_b32_e32 v108, s21, v178
	v_and_b32_e32 v109, s21, v179
	v_exp_f32_e32 v184, v106
	v_exp_f32_e32 v185, v108
	v_exp_f32_e32 v186, v107
	v_exp_f32_e32 v187, v109
	s_waitcnt lgkmcnt(4)
	v_exp_f32_e32 v243, v240
	v_fma_f32 v245, v241, v242, v170
	v_add_f32_e32 v153, v153, v240
	v_fma_f32 v244, v170, v243, v241
	v_cndmask_b32_e64 v170, v245, v244, s[40:41]
	ds_bpermute_b32 v240, v130, v153
	v_exp_f32_e32 v242, v153
	ds_bpermute_b32 v241, v130, v170
	v_fma_f32 v180, -v184, v184, 1.0
	v_fma_f32 v181, -v185, v185, 1.0
	v_fma_f32 v182, -v186, v186, 1.0
	v_fma_f32 v183, -v187, v187, 1.0
	v_sqrt_f32_e64 v180, |v180|
	v_sqrt_f32_e64 v181, |v181|
	v_sqrt_f32_e64 v182, |v182|
	v_sqrt_f32_e64 v183, |v183|
	v_mov_b32_dpp v188, v178 quad_perm:[1,0,3,2] row_mask:0xf bank_mask:0xf bound_ctrl:1
	v_mov_b32_dpp v165, v179 quad_perm:[1,0,3,2] row_mask:0xf bank_mask:0xf bound_ctrl:1
	v_pk_mul_f32 v[180:181], v[180:181], v[110:111]
	v_pk_mul_f32 v[182:183], v[182:183], v[112:113]
	v_perm_b32 v206, v188, v178, v125
	v_perm_b32 v207, v165, v179, v125
	global_store_dword v126, v206, s[16:17] offset:0
	global_store_dword v127, v207, s[16:17] offset:0
	v_pk_mul_f32 v[180:181], v[180:181], v[144:145]
	v_pk_mul_f32 v[182:183], v[182:183], v[146:147]
	v_pk_add_f32 v[106:107], v[106:107], v[108:109]
	v_cvt_pk_bf16_f32 v110, v180, v181
	v_cvt_pk_bf16_f32 v111, v182, v183
	v_add_f32_e32 v154, v106, v107
	v_lshlrev_b32_e32 v180, 16, v110
	v_mov_b32_dpp v188, v110 quad_perm:[1,0,3,2] row_mask:0xf bank_mask:0xf bound_ctrl:1
	v_and_b32_e32 v181, s21, v110
	v_mov_b32_dpp v165, v111 quad_perm:[1,0,3,2] row_mask:0xf bank_mask:0xf bound_ctrl:1
	v_lshlrev_b32_e32 v182, 16, v111
	v_and_b32_e32 v183, s21, v111
	v_perm_b32 v208, v188, v110, v125
	v_perm_b32 v209, v165, v111, v125
	global_store_dword v126, v208, s[18:19] offset:0
	global_store_dword v127, v209, s[18:19] offset:0
	s_add_u32 s16, s16, 0x10000
	s_addc_u32 s17, s17, 0
	s_add_u32 s18, s18, 0x10000
	s_addc_u32 s19, s19, 0
	v_fma_f32 v214, v180, v185, v181
	v_fma_f32 v215, v183, v186, v182
	v_fma_f32 v214, v214, v186, v182
	v_fma_f32 v215, v215, v185, v181
	v_fma_f32 v214, v214, v187, v183
	v_fma_f32 v215, v215, v184, v180
	ds_bpermute_b32 v210, v129, v154
	v_cndmask_b32_e64 v171, v215, v214, s[30:31]
	v_exp_f32_e32 v212, v154
	ds_bpermute_b32 v211, v129, v171
	s_waitcnt lgkmcnt(2)
	v_exp_f32_e32 v243, v240
	v_fma_f32 v245, v241, v242, v170
	v_add_f32_e32 v153, v153, v240
	v_fma_f32 v244, v170, v243, v241
	v_cndmask_b32_e64 v170, v245, v244, s[38:39]
	ds_read_u16_d16_hi v144, v123 offset:33792
	ds_read_u16_d16_hi v145, v123 offset:34320
	ds_read_u16_d16_hi v146, v123 offset:34848
	ds_read_u16_d16_hi v147, v123 offset:35376
	v_min_f32_e32 v102, s20, v102
	v_min_f32_e32 v103, s20, v103
	v_min_f32_e32 v104, s20, v104
	v_min_f32_e32 v105, s20, v105
	v_min_f32_e32 v98, s20, v98
	v_min_f32_e32 v99, s20, v99
	v_min_f32_e32 v100, s20, v100
	v_min_f32_e32 v101, s20, v101
	v_exp_f32_e32 v102, v102
	v_exp_f32_e32 v103, v103
	v_exp_f32_e32 v104, v104
	v_exp_f32_e32 v105, v105
	v_exp_f32_e32 v98, v98
	v_exp_f32_e32 v99, v99
	v_exp_f32_e32 v100, v100
	v_exp_f32_e32 v101, v101
	v_pk_add_f32 v[102:103], v[102:103], 1.0 op_sel_hi:[1,0]
	v_pk_add_f32 v[104:105], v[104:105], 1.0 op_sel_hi:[1,0]
	v_pk_add_f32 v[98:99], v[98:99], 1.0 op_sel_hi:[1,0]
	v_pk_add_f32 v[100:101], v[100:101], 1.0 op_sel_hi:[1,0]
	v_pk_mul_f32 v[216:217], v[102:103], v[98:99]
	v_pk_mul_f32 v[218:219], v[104:105], v[100:101]
	v_rcp_f32_e32 v216, v216
	v_rcp_f32_e32 v217, v217
	v_rcp_f32_e32 v218, v218
	v_rcp_f32_e32 v219, v219
	v_pk_mul_f32 v[98:99], v[98:99], v[216:217]
	v_pk_mul_f32 v[100:101], v[100:101], v[218:219]
	v_pk_mul_f32 v[102:103], v[102:103], v[216:217]
	v_pk_mul_f32 v[104:105], v[104:105], v[218:219]
	v_pk_mul_f32 v[98:99], v[98:99], v[132:133] op_sel_hi:[1,0]
	v_pk_mul_f32 v[100:101], v[100:101], v[132:133] op_sel_hi:[1,0]
	v_cvt_pk_bf16_f32 v216, v98, v99
	v_cvt_pk_bf16_f32 v217, v100, v101
	v_lshlrev_b32_e32 v98, 16, v216
	v_lshlrev_b32_e32 v99, 16, v217
	v_and_b32_e32 v100, s21, v216
	v_and_b32_e32 v101, s21, v217
	v_exp_f32_e32 v222, v98
	v_exp_f32_e32 v223, v100
	v_exp_f32_e32 v224, v99
	v_exp_f32_e32 v225, v101
	s_waitcnt lgkmcnt(4)
; #define LAS __attribute__((address_space(3)))
; __device__ __forceinline__ void p_rg_fused(const Frame& F0, const bf16* URAW, int L, const float* cw, const float* cbias, const bf16* Wg, const float* ba, const float* bx, const float* spt,
;                                            bf16* LA, bf16* INP, float* HEND, float* PROD) {
;     ...
;                 for (int m = 0; m < 8; ++m) {
;                     float lr[4], xr[4], ea[4]; unsigned lwv[4], xwv[4];
;                     int gq = g; asm volatile("" : "+v"(gq));
;                     {
;                         f32x4 u4;
; #pragma unroll
;                         for (int e = 0; e < 4; ++e) u4[e] = bf2f(*(const LAS bf16*)(ut + (16 * m + 4 * gq + e) * RGF_PITCH + cl * 2));
;                         const f32x4 na = acc[m][np], nb2 = acc[m][2 + np]; f32x4 e1, e2;
; #pragma unroll
;                         for (int e = 0; e < 4; ++e) { e1[e] = fexp2_(fminf(na[e], 115.f)); e2[e] = fexp2_(fminf(nb2[e], 115.f)); }
;                         const f32x4 d1 = e1 + 1.0f, d2 = e2 + 1.0f, dp = d1 * d2; f32x4 rc;
; #pragma unroll
;                         for (int e = 0; e < 4; ++e) rc[e] = frcp_(dp[e]);
;                         const f32x4 l4 = (d2 * rc) * psp, ig = d1 * rc;
;                         const unsigned lw01 = pk2(l4[0], l4[1]), lw23 = pk2(l4[2], l4[3]);
;                         lr[0] = bflo(lw01); lr[1] = bfhi(lw01); lr[2] = bflo(lw23); lr[3] = bfhi(lw23);
;                         f32x4 ea4, sq;
; #pragma unroll
;                         for (int e = 0; e < 4; ++e) { ea4[e] = fexp2_(lr[e]); ea[e] = ea4[e]; }
; #pragma unroll
;                         for (int e = 0; e < 4; ++e) sq[e] = fsqrt_(__builtin_fabsf(__builtin_fmaf(-ea4[e], ea4[e], 1.0f)));
;                         const f32x4 x4 = sq * ig * u4;
;                         const unsigned xw01 = pk2(x4[0], x4[1]), xw23 = pk2(x4[2], x4[3]);
;                         xr[0] = bflo(xw01); xr[1] = bfhi(xw01); xr[2] = bflo(xw23); xr[3] = bfhi(xw23);
;                         lwv[0] = lw01 & 0xffffu; lwv[1] = lw01 >> 16; lwv[2] = lw23 & 0xffffu; lwv[3] = lw23 >> 16;
;                         xwv[0] = xw01 & 0xffffu; xwv[1] = xw01 >> 16; xwv[2] = xw23 & 0xffffu; xwv[3] = xw23 >> 16; }
; #pragma unroll
;                     for (int ep = 0; ep < 2; ++ep) { const bool odd = (Lq & 1) != 0; const int tok = 16 * m + 4 * gq + 2 * ep + (odd ? 1 : 0);
	v_exp_f32_e32 v213, v210
	v_fma_f32 v215, v211, v212, v171
	v_add_f32_e32 v154, v154, v210
	v_fma_f32 v214, v171, v213, v211
	v_cndmask_b32_e64 v171, v215, v214, s[40:41]
	ds_bpermute_b32 v210, v130, v154
	v_exp_f32_e32 v212, v154
	ds_bpermute_b32 v211, v130, v171
	v_fma_f32 v218, -v222, v222, 1.0
	v_fma_f32 v219, -v223, v223, 1.0
	v_fma_f32 v220, -v224, v224, 1.0
	v_fma_f32 v221, -v225, v225, 1.0
	v_sqrt_f32_e64 v218, |v218|
	v_sqrt_f32_e64 v219, |v219|
	v_sqrt_f32_e64 v220, |v220|
	v_sqrt_f32_e64 v221, |v221|
	v_mov_b32_dpp v166, v216 quad_perm:[1,0,3,2] row_mask:0xf bank_mask:0xf bound_ctrl:1
	v_mov_b32_dpp v167, v217 quad_perm:[1,0,3,2] row_mask:0xf bank_mask:0xf bound_ctrl:1
	v_pk_mul_f32 v[218:219], v[218:219], v[102:103]
	v_pk_mul_f32 v[220:221], v[220:221], v[104:105]
	v_perm_b32 v236, v166, v216, v125
	v_perm_b32 v237, v167, v217, v125
	global_store_dword v126, v236, s[16:17] offset:0
	global_store_dword v127, v237, s[16:17] offset:0
	v_pk_mul_f32 v[218:219], v[218:219], v[148:149]
	v_pk_mul_f32 v[220:221], v[220:221], v[150:151]
	v_pk_add_f32 v[98:99], v[98:99], v[100:101]
	v_cvt_pk_bf16_f32 v102, v218, v219
	v_cvt_pk_bf16_f32 v103, v220, v221
	v_add_f32_e32 v155, v98, v99
	v_lshlrev_b32_e32 v218, 16, v102
	v_mov_b32_dpp v166, v102 quad_perm:[1,0,3,2] row_mask:0xf bank_mask:0xf bound_ctrl:1
	v_and_b32_e32 v219, s21, v102
	v_mov_b32_dpp v167, v103 quad_perm:[1,0,3,2] row_mask:0xf bank_mask:0xf bound_ctrl:1
	v_lshlrev_b32_e32 v220, 16, v103
	v_and_b32_e32 v221, s21, v103
	v_perm_b32 v238, v166, v102, v125
	v_perm_b32 v239, v167, v103, v125
	global_store_dword v126, v238, s[18:19] offset:0
	global_store_dword v127, v239, s[18:19] offset:0
	s_add_u32 s16, s16, 0x10000
	s_addc_u32 s17, s17, 0
	s_add_u32 s18, s18, 0x10000
	s_addc_u32 s19, s19, 0
	v_fma_f32 v244, v218, v223, v219
	v_fma_f32 v245, v221, v224, v220
	v_fma_f32 v244, v244, v224, v220
	v_fma_f32 v245, v245, v223, v219
	v_fma_f32 v244, v244, v225, v221
	v_fma_f32 v245, v245, v222, v218
	ds_bpermute_b32 v240, v129, v155
	v_cndmask_b32_e64 v172, v245, v244, s[30:31]
	v_exp_f32_e32 v242, v155
	ds_bpermute_b32 v241, v129, v172
	s_waitcnt lgkmcnt(2)
	v_exp_f32_e32 v213, v210
	v_fma_f32 v215, v211, v212, v171
	v_add_f32_e32 v154, v154, v210
	v_fma_f32 v214, v171, v213, v211
	v_cndmask_b32_e64 v171, v215, v214, s[38:39]
	ds_read_u16_d16_hi v148, v123 offset:42240
	ds_read_u16_d16_hi v149, v123 offset:42768
	ds_read_u16_d16_hi v150, v123 offset:43296
	ds_read_u16_d16_hi v151, v123 offset:43824
	v_min_f32_e32 v94, s20, v94
	v_min_f32_e32 v95, s20, v95
	v_min_f32_e32 v96, s20, v96
	v_min_f32_e32 v97, s20, v97
	v_min_f32_e32 v90, s20, v90
	v_min_f32_e32 v91, s20, v91
	v_min_f32_e32 v92, s20, v92
	v_min_f32_e32 v93, s20, v93
	v_exp_f32_e32 v94, v94
	v_exp_f32_e32 v95, v95
	v_exp_f32_e32 v96, v96
	v_exp_f32_e32 v97, v97
	v_exp_f32_e32 v90, v90
	v_exp_f32_e32 v91, v91
	v_exp_f32_e32 v92, v92
	v_exp_f32_e32 v93, v93
	v_pk_add_f32 v[94:95], v[94:95], 1.0 op_sel_hi:[1,0]
	v_pk_add_f32 v[96:97], v[96:97], 1.0 op_sel_hi:[1,0]
	v_pk_add_f32 v[90:91], v[90:91], 1.0 op_sel_hi:[1,0]
	v_pk_add_f32 v[92:93], v[92:93], 1.0 op_sel_hi:[1,0]
	v_pk_mul_f32 v[178:179], v[94:95], v[90:91]
	v_pk_mul_f32 v[180:181], v[96:97], v[92:93]
	v_rcp_f32_e32 v178, v178
	v_rcp_f32_e32 v179, v179
	v_rcp_f32_e32 v180, v180
	v_rcp_f32_e32 v181, v181
	v_pk_mul_f32 v[90:91], v[90:91], v[178:179]
	v_pk_mul_f32 v[92:93], v[92:93], v[180:181]
	v_pk_mul_f32 v[94:95], v[94:95], v[178:179]
	v_pk_mul_f32 v[96:97], v[96:97], v[180:181]
	v_pk_mul_f32 v[90:91], v[90:91], v[132:133] op_sel_hi:[1,0]
	v_pk_mul_f32 v[92:93], v[92:93], v[132:133] op_sel_hi:[1,0]
	v_cvt_pk_bf16_f32 v178, v90, v91
	v_cvt_pk_bf16_f32 v179, v92, v93
	v_lshlrev_b32_e32 v90, 16, v178
	v_lshlrev_b32_e32 v91, 16, v179
	v_and_b32_e32 v92, s21, v178
	v_and_b32_e32 v93, s21, v179
	v_exp_f32_e32 v184, v90
	v_exp_f32_e32 v185, v92
	v_exp_f32_e32 v186, v91
	v_exp_f32_e32 v187, v93
	s_waitcnt lgkmcnt(4)
	v_exp_f32_e32 v243, v240
	v_fma_f32 v245, v241, v242, v172
	v_add_f32_e32 v155, v155, v240
	v_fma_f32 v244, v172, v243, v241
	v_cndmask_b32_e64 v172, v245, v244, s[40:41]
	ds_bpermute_b32 v240, v130, v155
	v_exp_f32_e32 v242, v155
	ds_bpermute_b32 v241, v130, v172
	v_fma_f32 v180, -v184, v184, 1.0
	v_fma_f32 v181, -v185, v185, 1.0
	v_fma_f32 v182, -v186, v186, 1.0
	v_fma_f32 v183, -v187, v187, 1.0
	v_sqrt_f32_e64 v180, |v180|
	v_sqrt_f32_e64 v181, |v181|
	v_sqrt_f32_e64 v182, |v182|
	v_sqrt_f32_e64 v183, |v183|
	v_mov_b32_dpp v188, v178 quad_perm:[1,0,3,2] row_mask:0xf bank_mask:0xf bound_ctrl:1
	v_mov_b32_dpp v165, v179 quad_perm:[1,0,3,2] row_mask:0xf bank_mask:0xf bound_ctrl:1
	v_pk_mul_f32 v[180:181], v[180:181], v[94:95]
	v_pk_mul_f32 v[182:183], v[182:183], v[96:97]
	v_perm_b32 v206, v188, v178, v125
	v_perm_b32 v207, v165, v179, v125
	global_store_dword v126, v206, s[16:17] offset:0
	global_store_dword v127, v207, s[16:17] offset:0
	v_pk_mul_f32 v[180:181], v[180:181], v[144:145]
	v_pk_mul_f32 v[182:183], v[182:183], v[146:147]
	v_pk_add_f32 v[90:91], v[90:91], v[92:93]
	v_cvt_pk_bf16_f32 v94, v180, v181
	v_cvt_pk_bf16_f32 v95, v182, v183
	v_add_f32_e32 v156, v90, v91
	v_lshlrev_b32_e32 v180, 16, v94
	v_mov_b32_dpp v188, v94 quad_perm:[1,0,3,2] row_mask:0xf bank_mask:0xf bound_ctrl:1
	v_and_b32_e32 v181, s21, v94
	v_mov_b32_dpp v165, v95 quad_perm:[1,0,3,2] row_mask:0xf bank_mask:0xf bound_ctrl:1
	v_lshlrev_b32_e32 v182, 16, v95
	v_and_b32_e32 v183, s21, v95
	v_perm_b32 v208, v188, v94, v125
	v_perm_b32 v209, v165, v95, v125
	global_store_dword v126, v208, s[18:19] offset:0
	global_store_dword v127, v209, s[18:19] offset:0
	s_add_u32 s16, s16, 0x10000
	s_addc_u32 s17, s17, 0
	s_add_u32 s18, s18, 0x10000
	s_addc_u32 s19, s19, 0
	v_fma_f32 v214, v180, v185, v181
	v_fma_f32 v215, v183, v186, v182
	v_fma_f32 v214, v214, v186, v182
	v_fma_f32 v215, v215, v185, v181
	v_fma_f32 v214, v214, v187, v183
	v_fma_f32 v215, v215, v184, v180
	ds_bpermute_b32 v210, v129, v156
	v_cndmask_b32_e64 v173, v215, v214, s[30:31]
	v_exp_f32_e32 v212, v156
	ds_bpermute_b32 v211, v129, v173
	s_waitcnt lgkmcnt(2)
; #define LAS __attribute__((address_space(3)))
; __device__ __forceinline__ void p_rg_fused(const Frame& F0, const bf16* URAW, int L, const float* cw, const float* cbias, const bf16* Wg, const float* ba, const float* bx, const float* spt,
;                                            bf16* LA, bf16* INP, float* HEND, float* PROD) {
;     ...
;                 for (int m = 0; m < 8; ++m) {
;                     float lr[4], xr[4], ea[4]; unsigned lwv[4], xwv[4];
;                     int gq = g; asm volatile("" : "+v"(gq));
;                     {
;                         f32x4 u4;
; #pragma unroll
;                         for (int e = 0; e < 4; ++e) u4[e] = bf2f(*(const LAS bf16*)(ut + (16 * m + 4 * gq + e) * RGF_PITCH + cl * 2));
;                         const f32x4 na = acc[m][np], nb2 = acc[m][2 + np]; f32x4 e1, e2;
; #pragma unroll
;                         for (int e = 0; e < 4; ++e) { e1[e] = fexp2_(fminf(na[e], 115.f)); e2[e] = fexp2_(fminf(nb2[e], 115.f)); }
;                         const f32x4 d1 = e1 + 1.0f, d2 = e2 + 1.0f, dp = d1 * d2; f32x4 rc;
; #pragma unroll
;                         for (int e = 0; e < 4; ++e) rc[e] = frcp_(dp[e]);
;                         const f32x4 l4 = (d2 * rc) * psp, ig = d1 * rc;
;                         const unsigned lw01 = pk2(l4[0], l4[1]), lw23 = pk2(l4[2], l4[3]);
;                         lr[0] = bflo(lw01); lr[1] = bfhi(lw01); lr[2] = bflo(lw23); lr[3] = bfhi(lw23);
;                         f32x4 ea4, sq;
; #pragma unroll
;                         for (int e = 0; e < 4; ++e) { ea4[e] = fexp2_(lr[e]); ea[e] = ea4[e]; }
; #pragma unroll
;                         for (int e = 0; e < 4; ++e) sq[e] = fsqrt_(__builtin_fabsf(__builtin_fmaf(-ea4[e], ea4[e], 1.0f)));
;                         const f32x4 x4 = sq * ig * u4;
;                         const unsigned xw01 = pk2(x4[0], x4[1]), xw23 = pk2(x4[2], x4[3]);
;                         xr[0] = bflo(xw01); xr[1] = bfhi(xw01); xr[2] = bflo(xw23); xr[3] = bfhi(xw23);
;                         lwv[0] = lw01 & 0xffffu; lwv[1] = lw01 >> 16; lwv[2] = lw23 & 0xffffu; lwv[3] = lw23 >> 16;
;                         xwv[0] = xw01 & 0xffffu; xwv[1] = xw01 >> 16; xwv[2] = xw23 & 0xffffu; xwv[3] = xw23 >> 16; }
; #pragma unroll
;                     for (int ep = 0; ep < 2; ++ep) { const bool odd = (Lq & 1) != 0; const int tok = 16 * m + 4 * gq + 2 * ep + (odd ? 1 : 0);
	v_exp_f32_e32 v243, v240
	v_fma_f32 v245, v241, v242, v172
	v_add_f32_e32 v155, v155, v240
	v_fma_f32 v244, v172, v243, v241
	v_cndmask_b32_e64 v172, v245, v244, s[38:39]
	ds_read_u16_d16_hi v144, v123 offset:50688
	ds_read_u16_d16_hi v145, v123 offset:51216
	ds_read_u16_d16_hi v146, v123 offset:51744
	ds_read_u16_d16_hi v147, v123 offset:52272
	v_min_f32_e32 v86, s20, v86
	v_min_f32_e32 v87, s20, v87
	v_min_f32_e32 v88, s20, v88
	v_min_f32_e32 v89, s20, v89
	v_min_f32_e32 v82, s20, v82
	v_min_f32_e32 v83, s20, v83
	v_min_f32_e32 v84, s20, v84
	v_min_f32_e32 v85, s20, v85
	v_exp_f32_e32 v86, v86
	v_exp_f32_e32 v87, v87
	v_exp_f32_e32 v88, v88
	v_exp_f32_e32 v89, v89
	v_exp_f32_e32 v82, v82
	v_exp_f32_e32 v83, v83
	v_exp_f32_e32 v84, v84
	v_exp_f32_e32 v85, v85
	v_pk_add_f32 v[86:87], v[86:87], 1.0 op_sel_hi:[1,0]
	v_pk_add_f32 v[88:89], v[88:89], 1.0 op_sel_hi:[1,0]
	v_pk_add_f32 v[82:83], v[82:83], 1.0 op_sel_hi:[1,0]
	v_pk_add_f32 v[84:85], v[84:85], 1.0 op_sel_hi:[1,0]
	v_pk_mul_f32 v[216:217], v[86:87], v[82:83]
	v_pk_mul_f32 v[218:219], v[88:89], v[84:85]
	v_rcp_f32_e32 v216, v216
	v_rcp_f32_e32 v217, v217
	v_rcp_f32_e32 v218, v218
	v_rcp_f32_e32 v219, v219
	v_pk_mul_f32 v[82:83], v[82:83], v[216:217]
	v_pk_mul_f32 v[84:85], v[84:85], v[218:219]
	v_pk_mul_f32 v[86:87], v[86:87], v[216:217]
	v_pk_mul_f32 v[88:89], v[88:89], v[218:219]
	v_pk_mul_f32 v[82:83], v[82:83], v[132:133] op_sel_hi:[1,0]
	v_pk_mul_f32 v[84:85], v[84:85], v[132:133] op_sel_hi:[1,0]
	v_cvt_pk_bf16_f32 v216, v82, v83
	v_cvt_pk_bf16_f32 v217, v84, v85
	v_lshlrev_b32_e32 v82, 16, v216
	v_lshlrev_b32_e32 v83, 16, v217
	v_and_b32_e32 v84, s21, v216
	v_and_b32_e32 v85, s21, v217
	v_exp_f32_e32 v222, v82
	v_exp_f32_e32 v223, v84
	v_exp_f32_e32 v224, v83
	v_exp_f32_e32 v225, v85
	s_waitcnt lgkmcnt(4)
	v_exp_f32_e32 v213, v210
	v_fma_f32 v215, v211, v212, v173
	v_add_f32_e32 v156, v156, v210
	v_fma_f32 v214, v173, v213, v211
	v_cndmask_b32_e64 v173, v215, v214, s[40:41]
	ds_bpermute_b32 v210, v130, v156
	v_exp_f32_e32 v212, v156
	ds_bpermute_b32 v211, v130, v173
	v_fma_f32 v218, -v222, v222, 1.0
	v_fma_f32 v219, -v223, v223, 1.0
	v_fma_f32 v220, -v224, v224, 1.0
	v_fma_f32 v221, -v225, v225, 1.0
	v_sqrt_f32_e64 v218, |v218|
	v_sqrt_f32_e64 v219, |v219|
	v_sqrt_f32_e64 v220, |v220|
	v_sqrt_f32_e64 v221, |v221|
	v_mov_b32_dpp v166, v216 quad_perm:[1,0,3,2] row_mask:0xf bank_mask:0xf bound_ctrl:1
	v_mov_b32_dpp v167, v217 quad_perm:[1,0,3,2] row_mask:0xf bank_mask:0xf bound_ctrl:1
	v_pk_mul_f32 v[218:219], v[218:219], v[86:87]
	v_pk_mul_f32 v[220:221], v[220:221], v[88:89]
	v_perm_b32 v236, v166, v216, v125
	v_perm_b32 v237, v167, v217, v125
	global_store_dword v126, v236, s[16:17] offset:0
	global_store_dword v127, v237, s[16:17] offset:0
	v_pk_mul_f32 v[218:219], v[218:219], v[148:149]
	v_pk_mul_f32 v[220:221], v[220:221], v[150:151]
	v_pk_add_f32 v[82:83], v[82:83], v[84:85]
	v_cvt_pk_bf16_f32 v86, v218, v219
	v_cvt_pk_bf16_f32 v87, v220, v221
	v_add_f32_e32 v157, v82, v83
	v_lshlrev_b32_e32 v218, 16, v86
	v_mov_b32_dpp v166, v86 quad_perm:[1,0,3,2] row_mask:0xf bank_mask:0xf bound_ctrl:1
	v_and_b32_e32 v219, s21, v86
	v_mov_b32_dpp v167, v87 quad_perm:[1,0,3,2] row_mask:0xf bank_mask:0xf bound_ctrl:1
	v_lshlrev_b32_e32 v220, 16, v87
	v_and_b32_e32 v221, s21, v87
	v_perm_b32 v238, v166, v86, v125
	v_perm_b32 v239, v167, v87, v125
	global_store_dword v126, v238, s[18:19] offset:0
	global_store_dword v127, v239, s[18:19] offset:0
	s_add_u32 s16, s16, 0x10000
	s_addc_u32 s17, s17, 0
	s_add_u32 s18, s18, 0x10000
	s_addc_u32 s19, s19, 0
	v_fma_f32 v244, v218, v223, v219
	v_fma_f32 v245, v221, v224, v220
	v_fma_f32 v244, v244, v224, v220
	v_fma_f32 v245, v245, v223, v219
	v_fma_f32 v244, v244, v225, v221
	v_fma_f32 v245, v245, v222, v218
	ds_bpermute_b32 v240, v129, v157
	v_cndmask_b32_e64 v174, v245, v244, s[30:31]
	v_exp_f32_e32 v242, v157
	ds_bpermute_b32 v241, v129, v174
	s_waitcnt lgkmcnt(2)
	v_exp_f32_e32 v213, v210
	v_fma_f32 v215, v211, v212, v173
	v_add_f32_e32 v156, v156, v210
	v_fma_f32 v214, v173, v213, v211
	v_cndmask_b32_e64 v173, v215, v214, s[38:39]
	ds_read_u16_d16_hi v148, v123 offset:59136
	ds_read_u16_d16_hi v149, v123 offset:59664
	ds_read_u16_d16_hi v150, v123 offset:60192
	ds_read_u16_d16_hi v151, v123 offset:60720
	v_min_f32_e32 v78, s20, v78
	v_min_f32_e32 v79, s20, v79
	v_min_f32_e32 v80, s20, v80
	v_min_f32_e32 v81, s20, v81
	v_min_f32_e32 v74, s20, v74
	v_min_f32_e32 v75, s20, v75
	v_min_f32_e32 v76, s20, v76
	v_min_f32_e32 v77, s20, v77
	v_exp_f32_e32 v78, v78
	v_exp_f32_e32 v79, v79
	v_exp_f32_e32 v80, v80
	v_exp_f32_e32 v81, v81
	v_exp_f32_e32 v74, v74
	v_exp_f32_e32 v75, v75
	v_exp_f32_e32 v76, v76
	v_exp_f32_e32 v77, v77
	v_pk_add_f32 v[78:79], v[78:79], 1.0 op_sel_hi:[1,0]
	v_pk_add_f32 v[80:81], v[80:81], 1.0 op_sel_hi:[1,0]
	v_pk_add_f32 v[74:75], v[74:75], 1.0 op_sel_hi:[1,0]
	v_pk_add_f32 v[76:77], v[76:77], 1.0 op_sel_hi:[1,0]
	v_pk_mul_f32 v[178:179], v[78:79], v[74:75]
	v_pk_mul_f32 v[180:181], v[80:81], v[76:77]
	v_rcp_f32_e32 v178, v178
	v_rcp_f32_e32 v179, v179
	v_rcp_f32_e32 v180, v180
	v_rcp_f32_e32 v181, v181
	v_pk_mul_f32 v[74:75], v[74:75], v[178:179]
	v_pk_mul_f32 v[76:77], v[76:77], v[180:181]
	v_pk_mul_f32 v[78:79], v[78:79], v[178:179]
	v_pk_mul_f32 v[80:81], v[80:81], v[180:181]
	v_pk_mul_f32 v[74:75], v[74:75], v[132:133] op_sel_hi:[1,0]
	v_pk_mul_f32 v[76:77], v[76:77], v[132:133] op_sel_hi:[1,0]
	v_cvt_pk_bf16_f32 v178, v74, v75
	v_cvt_pk_bf16_f32 v179, v76, v77
	v_lshlrev_b32_e32 v74, 16, v178
	v_lshlrev_b32_e32 v75, 16, v179
	v_and_b32_e32 v76, s21, v178
	v_and_b32_e32 v77, s21, v179
	v_exp_f32_e32 v184, v74
	v_exp_f32_e32 v185, v76
	v_exp_f32_e32 v186, v75
	v_exp_f32_e32 v187, v77
	s_waitcnt lgkmcnt(4)
; #define LAS __attribute__((address_space(3)))
; __device__ __forceinline__ void p_rg_fused(const Frame& F0, const bf16* URAW, int L, const float* cw, const float* cbias, const bf16* Wg, const float* ba, const float* bx, const float* spt,
;                                            bf16* LA, bf16* INP, float* HEND, float* PROD) {
;     ...
;                 for (int m = 0; m < 8; ++m) {
;                     float lr[4], xr[4], ea[4]; unsigned lwv[4], xwv[4];
;                     int gq = g; asm volatile("" : "+v"(gq));
;                     {
;                         f32x4 u4;
; #pragma unroll
;                         for (int e = 0; e < 4; ++e) u4[e] = bf2f(*(const LAS bf16*)(ut + (16 * m + 4 * gq + e) * RGF_PITCH + cl * 2));
;                         const f32x4 na = acc[m][np], nb2 = acc[m][2 + np]; f32x4 e1, e2;
; #pragma unroll
;                         for (int e = 0; e < 4; ++e) { e1[e] = fexp2_(fminf(na[e], 115.f)); e2[e] = fexp2_(fminf(nb2[e], 115.f)); }
;                         const f32x4 d1 = e1 + 1.0f, d2 = e2 + 1.0f, dp = d1 * d2; f32x4 rc;
; #pragma unroll
;                         for (int e = 0; e < 4; ++e) rc[e] = frcp_(dp[e]);
;                         const f32x4 l4 = (d2 * rc) * psp, ig = d1 * rc;
;                         const unsigned lw01 = pk2(l4[0], l4[1]), lw23 = pk2(l4[2], l4[3]);
;                         lr[0] = bflo(lw01); lr[1] = bfhi(lw01); lr[2] = bflo(lw23); lr[3] = bfhi(lw23);
;                         f32x4 ea4, sq;
; #pragma unroll
;                         for (int e = 0; e < 4; ++e) { ea4[e] = fexp2_(lr[e]); ea[e] = ea4[e]; }
; #pragma unroll
;                         for (int e = 0; e < 4; ++e) sq[e] = fsqrt_(__builtin_fabsf(__builtin_fmaf(-ea4[e], ea4[e], 1.0f)));
;                         const f32x4 x4 = sq * ig * u4;
;                         const unsigned xw01 = pk2(x4[0], x4[1]), xw23 = pk2(x4[2], x4[3]);
;                         xr[0] = bflo(xw01); xr[1] = bfhi(xw01); xr[2] = bflo(xw23); xr[3] = bfhi(xw23);
;                         lwv[0] = lw01 & 0xffffu; lwv[1] = lw01 >> 16; lwv[2] = lw23 & 0xffffu; lwv[3] = lw23 >> 16;
;                         xwv[0] = xw01 & 0xffffu; xwv[1] = xw01 >> 16; xwv[2] = xw23 & 0xffffu; xwv[3] = xw23 >> 16; }
; #pragma unroll
;                     for (int ep = 0; ep < 2; ++ep) { const bool odd = (Lq & 1) != 0; const int tok = 16 * m + 4 * gq + 2 * ep + (odd ? 1 : 0);
	v_exp_f32_e32 v243, v240
	v_fma_f32 v245, v241, v242, v174
	v_add_f32_e32 v157, v157, v240
	v_fma_f32 v244, v174, v243, v241
	v_cndmask_b32_e64 v174, v245, v244, s[40:41]
	ds_bpermute_b32 v240, v130, v157
	v_exp_f32_e32 v242, v157
	ds_bpermute_b32 v241, v130, v174
	v_fma_f32 v180, -v184, v184, 1.0
	v_fma_f32 v181, -v185, v185, 1.0
	v_fma_f32 v182, -v186, v186, 1.0
	v_fma_f32 v183, -v187, v187, 1.0
	v_sqrt_f32_e64 v180, |v180|
	v_sqrt_f32_e64 v181, |v181|
	v_sqrt_f32_e64 v182, |v182|
	v_sqrt_f32_e64 v183, |v183|
	v_mov_b32_dpp v188, v178 quad_perm:[1,0,3,2] row_mask:0xf bank_mask:0xf bound_ctrl:1
	v_mov_b32_dpp v165, v179 quad_perm:[1,0,3,2] row_mask:0xf bank_mask:0xf bound_ctrl:1
	v_pk_mul_f32 v[180:181], v[180:181], v[78:79]
	v_pk_mul_f32 v[182:183], v[182:183], v[80:81]
	v_perm_b32 v206, v188, v178, v125
	v_perm_b32 v207, v165, v179, v125
	global_store_dword v126, v206, s[16:17] offset:0
	global_store_dword v127, v207, s[16:17] offset:0
	v_pk_mul_f32 v[180:181], v[180:181], v[144:145]
	v_pk_mul_f32 v[182:183], v[182:183], v[146:147]
	v_pk_add_f32 v[74:75], v[74:75], v[76:77]
	v_cvt_pk_bf16_f32 v78, v180, v181
	v_cvt_pk_bf16_f32 v79, v182, v183
	v_add_f32_e32 v158, v74, v75
	v_lshlrev_b32_e32 v180, 16, v78
	v_mov_b32_dpp v188, v78 quad_perm:[1,0,3,2] row_mask:0xf bank_mask:0xf bound_ctrl:1
	v_and_b32_e32 v181, s21, v78
	v_mov_b32_dpp v165, v79 quad_perm:[1,0,3,2] row_mask:0xf bank_mask:0xf bound_ctrl:1
	v_lshlrev_b32_e32 v182, 16, v79
	v_and_b32_e32 v183, s21, v79
	v_perm_b32 v208, v188, v78, v125
	v_perm_b32 v209, v165, v79, v125
	global_store_dword v126, v208, s[18:19] offset:0
	global_store_dword v127, v209, s[18:19] offset:0
	s_add_u32 s16, s16, 0x10000
	s_addc_u32 s17, s17, 0
	s_add_u32 s18, s18, 0x10000
	s_addc_u32 s19, s19, 0
	v_fma_f32 v214, v180, v185, v181
	v_fma_f32 v215, v183, v186, v182
	v_fma_f32 v214, v214, v186, v182
	v_fma_f32 v215, v215, v185, v181
	v_fma_f32 v214, v214, v187, v183
	v_fma_f32 v215, v215, v184, v180
	ds_bpermute_b32 v210, v129, v158
	v_cndmask_b32_e64 v175, v215, v214, s[30:31]
	v_exp_f32_e32 v212, v158
	ds_bpermute_b32 v211, v129, v175
	s_waitcnt lgkmcnt(2)
	v_exp_f32_e32 v243, v240
	v_fma_f32 v245, v241, v242, v174
	v_add_f32_e32 v157, v157, v240
	v_fma_f32 v244, v174, v243, v241
	v_cndmask_b32_e64 v174, v245, v244, s[38:39]
	v_min_f32_e32 v70, s20, v70
	v_min_f32_e32 v71, s20, v71
	v_min_f32_e32 v72, s20, v72
	v_min_f32_e32 v73, s20, v73
	v_min_f32_e32 v66, s20, v66
	v_min_f32_e32 v67, s20, v67
	v_min_f32_e32 v68, s20, v68
	v_min_f32_e32 v69, s20, v69
	v_exp_f32_e32 v70, v70
	v_exp_f32_e32 v71, v71
	v_exp_f32_e32 v72, v72
	v_exp_f32_e32 v73, v73
	v_exp_f32_e32 v66, v66
	v_exp_f32_e32 v67, v67
	v_exp_f32_e32 v68, v68
	v_exp_f32_e32 v69, v69
	v_pk_add_f32 v[70:71], v[70:71], 1.0 op_sel_hi:[1,0]
	v_pk_add_f32 v[72:73], v[72:73], 1.0 op_sel_hi:[1,0]
	v_pk_add_f32 v[66:67], v[66:67], 1.0 op_sel_hi:[1,0]
	v_pk_add_f32 v[68:69], v[68:69], 1.0 op_sel_hi:[1,0]
	v_pk_mul_f32 v[216:217], v[70:71], v[66:67]
	v_pk_mul_f32 v[218:219], v[72:73], v[68:69]
	v_rcp_f32_e32 v216, v216
	v_rcp_f32_e32 v217, v217
	v_rcp_f32_e32 v218, v218
	v_rcp_f32_e32 v219, v219
	v_pk_mul_f32 v[66:67], v[66:67], v[216:217]
	v_pk_mul_f32 v[68:69], v[68:69], v[218:219]
	v_pk_mul_f32 v[70:71], v[70:71], v[216:217]
	v_pk_mul_f32 v[72:73], v[72:73], v[218:219]
	v_pk_mul_f32 v[66:67], v[66:67], v[132:133] op_sel_hi:[1,0]
	v_pk_mul_f32 v[68:69], v[68:69], v[132:133] op_sel_hi:[1,0]
	v_cvt_pk_bf16_f32 v216, v66, v67
	v_cvt_pk_bf16_f32 v217, v68, v69
	v_lshlrev_b32_e32 v66, 16, v216
	v_lshlrev_b32_e32 v67, 16, v217
	v_and_b32_e32 v68, s21, v216
	v_and_b32_e32 v69, s21, v217
	v_exp_f32_e32 v222, v66
	v_exp_f32_e32 v223, v68
	v_exp_f32_e32 v224, v67
	v_exp_f32_e32 v225, v69
	s_waitcnt lgkmcnt(0)
	v_exp_f32_e32 v213, v210
	v_fma_f32 v215, v211, v212, v175
	v_add_f32_e32 v158, v158, v210
	v_fma_f32 v214, v175, v213, v211
	v_cndmask_b32_e64 v175, v215, v214, s[40:41]
	ds_bpermute_b32 v210, v130, v158
	v_exp_f32_e32 v212, v158
	ds_bpermute_b32 v211, v130, v175
	v_fma_f32 v218, -v222, v222, 1.0
	v_fma_f32 v219, -v223, v223, 1.0
	v_fma_f32 v220, -v224, v224, 1.0
	v_fma_f32 v221, -v225, v225, 1.0
	v_sqrt_f32_e64 v218, |v218|
	v_sqrt_f32_e64 v219, |v219|
	v_sqrt_f32_e64 v220, |v220|
	v_sqrt_f32_e64 v221, |v221|
	v_mov_b32_dpp v166, v216 quad_perm:[1,0,3,2] row_mask:0xf bank_mask:0xf bound_ctrl:1
	v_mov_b32_dpp v167, v217 quad_perm:[1,0,3,2] row_mask:0xf bank_mask:0xf bound_ctrl:1
	v_pk_mul_f32 v[218:219], v[218:219], v[70:71]
	v_pk_mul_f32 v[220:221], v[220:221], v[72:73]
	v_perm_b32 v236, v166, v216, v125
	v_perm_b32 v237, v167, v217, v125
	global_store_dword v126, v236, s[16:17] offset:0
	global_store_dword v127, v237, s[16:17] offset:0
	v_pk_mul_f32 v[218:219], v[218:219], v[148:149]
	v_pk_mul_f32 v[220:221], v[220:221], v[150:151]
	v_pk_add_f32 v[66:67], v[66:67], v[68:69]
	v_cvt_pk_bf16_f32 v70, v218, v219
	v_cvt_pk_bf16_f32 v71, v220, v221
	v_add_f32_e32 v159, v66, v67
	v_lshlrev_b32_e32 v218, 16, v70
	v_mov_b32_dpp v166, v70 quad_perm:[1,0,3,2] row_mask:0xf bank_mask:0xf bound_ctrl:1
	v_and_b32_e32 v219, s21, v70
	v_mov_b32_dpp v167, v71 quad_perm:[1,0,3,2] row_mask:0xf bank_mask:0xf bound_ctrl:1
	v_lshlrev_b32_e32 v220, 16, v71
	v_and_b32_e32 v221, s21, v71
	v_perm_b32 v238, v166, v70, v125
	v_perm_b32 v239, v167, v71, v125
	global_store_dword v126, v238, s[18:19] offset:0
	global_store_dword v127, v239, s[18:19] offset:0
	v_fma_f32 v244, v218, v223, v219
	v_fma_f32 v245, v221, v224, v220
	v_fma_f32 v244, v244, v224, v220
	v_fma_f32 v245, v245, v223, v219
	v_fma_f32 v244, v244, v225, v221
	v_fma_f32 v245, v245, v222, v218
	ds_bpermute_b32 v240, v129, v159
	v_cndmask_b32_e64 v176, v245, v244, s[30:31]
	v_exp_f32_e32 v242, v159
	ds_bpermute_b32 v241, v129, v176
	s_waitcnt lgkmcnt(2)
	v_exp_f32_e32 v213, v210
	v_fma_f32 v215, v211, v212, v175
	v_add_f32_e32 v158, v158, v210
	v_fma_f32 v214, v175, v213, v211
	v_cndmask_b32_e64 v175, v215, v214, s[38:39]
	s_waitcnt lgkmcnt(0)
	v_exp_f32_e32 v243, v240
	v_fma_f32 v245, v241, v242, v176
	v_add_f32_e32 v159, v159, v240
	v_fma_f32 v244, v176, v243, v241
	v_cndmask_b32_e64 v176, v245, v244, s[40:41]
	ds_bpermute_b32 v240, v130, v159
	v_exp_f32_e32 v242, v159
	ds_bpermute_b32 v241, v130, v176
	s_waitcnt lgkmcnt(0)
	v_exp_f32_e32 v243, v240
	v_fma_f32 v245, v241, v242, v176
	v_add_f32_e32 v159, v159, v240
	v_fma_f32 v244, v176, v243, v241
	v_cndmask_b32_e64 v176, v245, v244, s[38:39]
	v_add_f32_e32 v178, v152, v153
	v_add_f32_e32 v179, v154, v155
	v_add_f32_e32 v180, v156, v157
	v_add_f32_e32 v181, v158, v159
	v_add_f32_e32 v178, v178, v179
	v_add_f32_e32 v180, v180, v181
	v_exp_f32_e32 v178, v178
	v_exp_f32_e32 v180, v180
	s_cmp_lg_u32 s10, 0
	s_cbranch_scc1 .Lrgx_bwd_np0
; __device__ __forceinline__ void p_rg_fused(const Frame& F0, const bf16* URAW, int L, const float* cw, const float* cbias, const bf16* Wg, const float* ba, const float* bx, const float* spt,
;                                            bf16* LA, bf16* INP, float* HEND, float* PROD) {
;     ...
;             for (int np = 0; np < 2; ++np) {
;                 const int cl = 32 * w8 + 16 * np + l15, c = nb * 256 + cl;
;                 const float psp = spt[d * D + c];
;                 float Lm[8], Hm[8];
; #pragma unroll
;                 for (int m = 0; m < 8; ++m) {
;                     float lr[4], xr[4], ea[4]; unsigned lwv[4], xwv[4];
;                     int gq = g; asm volatile("" : "+v"(gq));
;                     {
;                         f32x4 u4;
; #pragma unroll
;                         for (int e = 0; e < 4; ++e) u4[e] = bf2f(*(const LAS bf16*)(ut + (16 * m + 4 * gq + e) * RGF_PITCH + cl * 2));
;                         const f32x4 na = acc[m][np], nb2 = acc[m][2 + np]; f32x4 e1, e2;
; #pragma unroll
;                         for (int e = 0; e < 4; ++e) { e1[e] = fexp2_(fminf(na[e], 115.f)); e2[e] = fexp2_(fminf(nb2[e], 115.f)); }
;                         const f32x4 d1 = e1 + 1.0f, d2 = e2 + 1.0f, dp = d1 * d2; f32x4 rc;
; #pragma unroll
;                         for (int e = 0; e < 4; ++e) rc[e] = frcp_(dp[e]);
;                         const f32x4 l4 = (d2 * rc) * psp, ig = d1 * rc;
;                         const unsigned lw01 = pk2(l4[0], l4[1]), lw23 = pk2(l4[2], l4[3]);
;     ...
;                 float Lc[2], Hc[2];
; #pragma unroll
;                 for (int ch = 0; ch < 2; ++ch) {
;                     if (d == 0) { float H = Hm[4 * ch]; H = H * fexp2_(Lm[4 * ch + 1]) + Hm[4 * ch + 1]; H = H * fexp2_(Lm[4 * ch + 2]) + Hm[4 * ch + 2]; H = H * fexp2_(Lm[4 * ch + 3]) + Hm[4 * ch + 3]; Hc[ch] = H; }
;                     else        { float H = Hm[4 * ch + 3]; H = H * fexp2_(Lm[4 * ch + 2]) + Hm[4 * ch + 2]; H = H * fexp2_(Lm[4 * ch + 1]) + Hm[4 * ch + 1]; H = H * fexp2_(Lm[4 * ch]) + Hm[4 * ch]; Hc[ch] = H; }
;                     Lc[ch] = (Lm[4 * ch] + Lm[4 * ch + 1]) + (Lm[4 * ch + 2] + Lm[4 * ch + 3]);
;                 }
;                 if (g == 0) {
; #pragma unroll
;                     for (int ch = 0; ch < 2; ++ch) { const size_t o = ((size_t)(run * 2 + ch) * 2 + d) * D + c; HEND[o] = Hc[ch]; PROD[o] = fexp2_(Lc[ch]); } }
	v_exp_f32_e32 v184, v153
	v_exp_f32_e32 v185, v154
	v_exp_f32_e32 v186, v155
	v_exp_f32_e32 v222, v157
	v_exp_f32_e32 v223, v158
	v_exp_f32_e32 v224, v159
	v_fma_f32 v214, v169, v184, v170
	v_fma_f32 v215, v173, v222, v174
	v_fma_f32 v214, v214, v185, v171
	v_fma_f32 v215, v215, v223, v175
	v_fma_f32 v214, v214, v186, v172
	v_fma_f32 v215, v215, v224, v176
	s_branch .Lrgx_st_np0
.Lrgx_bwd_np0:
	v_exp_f32_e32 v186, v154
	v_exp_f32_e32 v185, v153
	v_exp_f32_e32 v184, v152
	v_exp_f32_e32 v224, v158
	v_exp_f32_e32 v223, v157
	v_exp_f32_e32 v222, v156
	v_fma_f32 v214, v172, v186, v171
	v_fma_f32 v215, v176, v224, v175
	v_fma_f32 v214, v214, v185, v170
	v_fma_f32 v215, v215, v223, v174
	v_fma_f32 v214, v214, v184, v169
	v_fma_f32 v215, v215, v222, v173
.Lrgx_st_np0:
	s_lshl_b32 s22, s10, 13
	s_lshl_b64 s[0:1], s[24:25], 2
	s_add_u32 s0, s0, s22
	s_addc_u32 s1, s1, 0
	s_lshl_b64 s[16:17], s[26:27], 2
	s_add_u32 s16, s16, s22
	s_addc_u32 s17, s17, 0
	s_add_u32 s18, s8, s0
	s_addc_u32 s19, s9, s1
	s_add_u32 s0, s6, s0
	s_addc_u32 s1, s7, s1
	s_add_u32 s22, s8, s16
	s_addc_u32 s23, s9, s17
	s_add_u32 s16, s6, s16
	s_addc_u32 s17, s7, s17
	s_mov_b64 vcc, exec
	s_and_b64 exec, exec, s[42:43]
	global_store_dword v128, v214, s[18:19] offset:0
	global_store_dword v128, v178, s[0:1] offset:0
	global_store_dword v128, v215, s[22:23] offset:0
	global_store_dword v128, v180, s[16:17] offset:0
	s_mov_b64 exec, vcc
	s_lshl_b32 s0, s10, 25
	s_add_u32 s16, s61, s0
	s_addc_u32 s17, s71, 0
	s_add_u32 s18, s65, s0
	s_addc_u32 s19, s72, 0
	ds_read_u16_d16_hi v144, v123 offset:32
	ds_read_u16_d16_hi v145, v123 offset:560
	ds_read_u16_d16_hi v146, v123 offset:1088
	ds_read_u16_d16_hi v147, v123 offset:1616
	ds_read_u16_d16_hi v148, v123 offset:8480
	ds_read_u16_d16_hi v149, v123 offset:9008
	ds_read_u16_d16_hi v150, v123 offset:9536
	ds_read_u16_d16_hi v151, v123 offset:10064
	v_min_f32_e32 v62, s20, v62
	v_min_f32_e32 v63, s20, v63
	v_min_f32_e32 v64, s20, v64
	v_min_f32_e32 v65, s20, v65
	v_min_f32_e32 v58, s20, v58
	v_min_f32_e32 v59, s20, v59
	v_min_f32_e32 v60, s20, v60
	v_min_f32_e32 v61, s20, v61
	v_exp_f32_e32 v62, v62
	v_exp_f32_e32 v63, v63
	v_exp_f32_e32 v64, v64
	v_exp_f32_e32 v65, v65
	v_exp_f32_e32 v58, v58
	v_exp_f32_e32 v59, v59
	v_exp_f32_e32 v60, v60
	v_exp_f32_e32 v61, v61
	v_pk_add_f32 v[62:63], v[62:63], 1.0 op_sel_hi:[1,0]
	v_pk_add_f32 v[64:65], v[64:65], 1.0 op_sel_hi:[1,0]
	v_pk_add_f32 v[58:59], v[58:59], 1.0 op_sel_hi:[1,0]
	v_pk_add_f32 v[60:61], v[60:61], 1.0 op_sel_hi:[1,0]
	v_pk_mul_f32 v[178:179], v[62:63], v[58:59]
	v_pk_mul_f32 v[180:181], v[64:65], v[60:61]
	v_rcp_f32_e32 v178, v178
	v_rcp_f32_e32 v179, v179
	v_rcp_f32_e32 v180, v180
	v_rcp_f32_e32 v181, v181
	v_pk_mul_f32 v[58:59], v[58:59], v[178:179]
	v_pk_mul_f32 v[60:61], v[60:61], v[180:181]
	v_pk_mul_f32 v[62:63], v[62:63], v[178:179]
	v_pk_mul_f32 v[64:65], v[64:65], v[180:181]
	v_pk_mul_f32 v[58:59], v[58:59], v[134:135] op_sel_hi:[1,0]
	v_pk_mul_f32 v[60:61], v[60:61], v[134:135] op_sel_hi:[1,0]
	v_cvt_pk_bf16_f32 v178, v58, v59
	v_cvt_pk_bf16_f32 v179, v60, v61
	v_lshlrev_b32_e32 v58, 16, v178
	v_lshlrev_b32_e32 v59, 16, v179
	v_and_b32_e32 v60, s21, v178
	v_and_b32_e32 v61, s21, v179
	v_exp_f32_e32 v184, v58
	v_exp_f32_e32 v185, v60
	v_exp_f32_e32 v186, v59
	v_exp_f32_e32 v187, v61
	v_fma_f32 v180, -v184, v184, 1.0
	v_fma_f32 v181, -v185, v185, 1.0
	v_fma_f32 v182, -v186, v186, 1.0
	v_fma_f32 v183, -v187, v187, 1.0
	v_sqrt_f32_e64 v180, |v180|
	v_sqrt_f32_e64 v181, |v181|
	v_sqrt_f32_e64 v182, |v182|
	v_sqrt_f32_e64 v183, |v183|
	v_mov_b32_dpp v188, v178 quad_perm:[1,0,3,2] row_mask:0xf bank_mask:0xf bound_ctrl:1
	v_mov_b32_dpp v165, v179 quad_perm:[1,0,3,2] row_mask:0xf bank_mask:0xf bound_ctrl:1
	v_pk_mul_f32 v[180:181], v[180:181], v[62:63]
	v_pk_mul_f32 v[182:183], v[182:183], v[64:65]
	v_perm_b32 v206, v188, v178, v125
	v_perm_b32 v207, v165, v179, v125
	global_store_dword v126, v206, s[16:17] offset:32
	global_store_dword v127, v207, s[16:17] offset:32
	s_waitcnt lgkmcnt(4)
	v_pk_mul_f32 v[180:181], v[180:181], v[144:145]
	v_pk_mul_f32 v[182:183], v[182:183], v[146:147]
	v_pk_add_f32 v[58:59], v[58:59], v[60:61]
	v_cvt_pk_bf16_f32 v62, v180, v181
	v_cvt_pk_bf16_f32 v63, v182, v183
	v_add_f32_e32 v152, v58, v59
	v_lshlrev_b32_e32 v180, 16, v62
	v_mov_b32_dpp v188, v62 quad_perm:[1,0,3,2] row_mask:0xf bank_mask:0xf bound_ctrl:1
	v_and_b32_e32 v181, s21, v62
	v_mov_b32_dpp v165, v63 quad_perm:[1,0,3,2] row_mask:0xf bank_mask:0xf bound_ctrl:1
	v_lshlrev_b32_e32 v182, 16, v63
	v_and_b32_e32 v183, s21, v63
	v_perm_b32 v208, v188, v62, v125
	v_perm_b32 v209, v165, v63, v125
	global_store_dword v126, v208, s[18:19] offset:32
	global_store_dword v127, v209, s[18:19] offset:32
	s_add_u32 s16, s16, 0x10000
	s_addc_u32 s17, s17, 0
	s_add_u32 s18, s18, 0x10000
	s_addc_u32 s19, s19, 0
	v_fma_f32 v214, v180, v185, v181
	v_fma_f32 v215, v183, v186, v182
	v_fma_f32 v214, v214, v186, v182
	v_fma_f32 v215, v215, v185, v181
	v_fma_f32 v214, v214, v187, v183
	v_fma_f32 v215, v215, v184, v180
	ds_bpermute_b32 v210, v129, v152
	v_cndmask_b32_e64 v169, v215, v214, s[30:31]
	v_exp_f32_e32 v212, v152
	ds_bpermute_b32 v211, v129, v169
	ds_read_u16_d16_hi v144, v123 offset:16928
	ds_read_u16_d16_hi v145, v123 offset:17456
	ds_read_u16_d16_hi v146, v123 offset:17984
	ds_read_u16_d16_hi v147, v123 offset:18512
	v_min_f32_e32 v54, s20, v54
	v_min_f32_e32 v55, s20, v55
	v_min_f32_e32 v56, s20, v56
	v_min_f32_e32 v57, s20, v57
	v_min_f32_e32 v50, s20, v50
	v_min_f32_e32 v51, s20, v51
	v_min_f32_e32 v52, s20, v52
	v_min_f32_e32 v53, s20, v53
	v_exp_f32_e32 v54, v54
	v_exp_f32_e32 v55, v55
	v_exp_f32_e32 v56, v56
	v_exp_f32_e32 v57, v57
	v_exp_f32_e32 v50, v50
	v_exp_f32_e32 v51, v51
	v_exp_f32_e32 v52, v52
	v_exp_f32_e32 v53, v53
	v_pk_add_f32 v[54:55], v[54:55], 1.0 op_sel_hi:[1,0]
	v_pk_add_f32 v[56:57], v[56:57], 1.0 op_sel_hi:[1,0]
	v_pk_add_f32 v[50:51], v[50:51], 1.0 op_sel_hi:[1,0]
	v_pk_add_f32 v[52:53], v[52:53], 1.0 op_sel_hi:[1,0]
	v_pk_mul_f32 v[216:217], v[54:55], v[50:51]
	v_pk_mul_f32 v[218:219], v[56:57], v[52:53]
	v_rcp_f32_e32 v216, v216
	v_rcp_f32_e32 v217, v217
	v_rcp_f32_e32 v218, v218
	v_rcp_f32_e32 v219, v219
	v_pk_mul_f32 v[50:51], v[50:51], v[216:217]
	v_pk_mul_f32 v[52:53], v[52:53], v[218:219]
	v_pk_mul_f32 v[54:55], v[54:55], v[216:217]
	v_pk_mul_f32 v[56:57], v[56:57], v[218:219]
	v_pk_mul_f32 v[50:51], v[50:51], v[134:135] op_sel_hi:[1,0]
	v_pk_mul_f32 v[52:53], v[52:53], v[134:135] op_sel_hi:[1,0]
	v_cvt_pk_bf16_f32 v216, v50, v51
	v_cvt_pk_bf16_f32 v217, v52, v53
	v_lshlrev_b32_e32 v50, 16, v216
	v_lshlrev_b32_e32 v51, 16, v217
	v_and_b32_e32 v52, s21, v216
	v_and_b32_e32 v53, s21, v217
	v_exp_f32_e32 v222, v50
	v_exp_f32_e32 v223, v52
	v_exp_f32_e32 v224, v51
	v_exp_f32_e32 v225, v53
	s_waitcnt lgkmcnt(4)
; #define LAS __attribute__((address_space(3)))
; __device__ __forceinline__ void p_rg_fused(const Frame& F0, const bf16* URAW, int L, const float* cw, const float* cbias, const bf16* Wg, const float* ba, const float* bx, const float* spt,
;                                            bf16* LA, bf16* INP, float* HEND, float* PROD) {
;     ...
;                 for (int m = 0; m < 8; ++m) {
;                     float lr[4], xr[4], ea[4]; unsigned lwv[4], xwv[4];
;                     int gq = g; asm volatile("" : "+v"(gq));
;                     {
;                         f32x4 u4;
; #pragma unroll
;                         for (int e = 0; e < 4; ++e) u4[e] = bf2f(*(const LAS bf16*)(ut + (16 * m + 4 * gq + e) * RGF_PITCH + cl * 2));
;                         const f32x4 na = acc[m][np], nb2 = acc[m][2 + np]; f32x4 e1, e2;
; #pragma unroll
;                         for (int e = 0; e < 4; ++e) { e1[e] = fexp2_(fminf(na[e], 115.f)); e2[e] = fexp2_(fminf(nb2[e], 115.f)); }
;                         const f32x4 d1 = e1 + 1.0f, d2 = e2 + 1.0f, dp = d1 * d2; f32x4 rc;
; #pragma unroll
;                         for (int e = 0; e < 4; ++e) rc[e] = frcp_(dp[e]);
;                         const f32x4 l4 = (d2 * rc) * psp, ig = d1 * rc;
;                         const unsigned lw01 = pk2(l4[0], l4[1]), lw23 = pk2(l4[2], l4[3]);
;                         lr[0] = bflo(lw01); lr[1] = bfhi(lw01); lr[2] = bflo(lw23); lr[3] = bfhi(lw23);
;                         f32x4 ea4, sq;
; #pragma unroll
;                         for (int e = 0; e < 4; ++e) { ea4[e] = fexp2_(lr[e]); ea[e] = ea4[e]; }
; #pragma unroll
;                         for (int e = 0; e < 4; ++e) sq[e] = fsqrt_(__builtin_fabsf(__builtin_fmaf(-ea4[e], ea4[e], 1.0f)));
;                         const f32x4 x4 = sq * ig * u4;
;                         const unsigned xw01 = pk2(x4[0], x4[1]), xw23 = pk2(x4[2], x4[3]);
;                         xr[0] = bflo(xw01); xr[1] = bfhi(xw01); xr[2] = bflo(xw23); xr[3] = bfhi(xw23);
;                         lwv[0] = lw01 & 0xffffu; lwv[1] = lw01 >> 16; lwv[2] = lw23 & 0xffffu; lwv[3] = lw23 >> 16;
;                         xwv[0] = xw01 & 0xffffu; xwv[1] = xw01 >> 16; xwv[2] = xw23 & 0xffffu; xwv[3] = xw23 >> 16; }
; #pragma unroll
;                     for (int ep = 0; ep < 2; ++ep) { const bool odd = (Lq & 1) != 0; const int tok = 16 * m + 4 * gq + 2 * ep + (odd ? 1 : 0);
	v_exp_f32_e32 v213, v210
	v_fma_f32 v215, v211, v212, v169
	v_add_f32_e32 v152, v152, v210
	v_fma_f32 v214, v169, v213, v211
	v_cndmask_b32_e64 v169, v215, v214, s[40:41]
	ds_bpermute_b32 v210, v130, v152
	v_exp_f32_e32 v212, v152
	ds_bpermute_b32 v211, v130, v169
	v_fma_f32 v218, -v222, v222, 1.0
	v_fma_f32 v219, -v223, v223, 1.0
	v_fma_f32 v220, -v224, v224, 1.0
	v_fma_f32 v221, -v225, v225, 1.0
	v_sqrt_f32_e64 v218, |v218|
	v_sqrt_f32_e64 v219, |v219|
	v_sqrt_f32_e64 v220, |v220|
	v_sqrt_f32_e64 v221, |v221|
	v_mov_b32_dpp v166, v216 quad_perm:[1,0,3,2] row_mask:0xf bank_mask:0xf bound_ctrl:1
	v_mov_b32_dpp v167, v217 quad_perm:[1,0,3,2] row_mask:0xf bank_mask:0xf bound_ctrl:1
	v_pk_mul_f32 v[218:219], v[218:219], v[54:55]
	v_pk_mul_f32 v[220:221], v[220:221], v[56:57]
	v_perm_b32 v236, v166, v216, v125
	v_perm_b32 v237, v167, v217, v125
	global_store_dword v126, v236, s[16:17] offset:32
	global_store_dword v127, v237, s[16:17] offset:32
	v_pk_mul_f32 v[218:219], v[218:219], v[148:149]
	v_pk_mul_f32 v[220:221], v[220:221], v[150:151]
	v_pk_add_f32 v[50:51], v[50:51], v[52:53]
	v_cvt_pk_bf16_f32 v54, v218, v219
	v_cvt_pk_bf16_f32 v55, v220, v221
	v_add_f32_e32 v153, v50, v51
	v_lshlrev_b32_e32 v218, 16, v54
	v_mov_b32_dpp v166, v54 quad_perm:[1,0,3,2] row_mask:0xf bank_mask:0xf bound_ctrl:1
	v_and_b32_e32 v219, s21, v54
	v_mov_b32_dpp v167, v55 quad_perm:[1,0,3,2] row_mask:0xf bank_mask:0xf bound_ctrl:1
	v_lshlrev_b32_e32 v220, 16, v55
	v_and_b32_e32 v221, s21, v55
	v_perm_b32 v238, v166, v54, v125
	v_perm_b32 v239, v167, v55, v125
	global_store_dword v126, v238, s[18:19] offset:32
	global_store_dword v127, v239, s[18:19] offset:32
	s_add_u32 s16, s16, 0x10000
	s_addc_u32 s17, s17, 0
	s_add_u32 s18, s18, 0x10000
	s_addc_u32 s19, s19, 0
	v_fma_f32 v244, v218, v223, v219
	v_fma_f32 v245, v221, v224, v220
	v_fma_f32 v244, v244, v224, v220
	v_fma_f32 v245, v245, v223, v219
	v_fma_f32 v244, v244, v225, v221
	v_fma_f32 v245, v245, v222, v218
	ds_bpermute_b32 v240, v129, v153
	v_cndmask_b32_e64 v170, v245, v244, s[30:31]
	v_exp_f32_e32 v242, v153
	ds_bpermute_b32 v241, v129, v170
	s_waitcnt lgkmcnt(2)
	v_exp_f32_e32 v213, v210
	v_fma_f32 v215, v211, v212, v169
	v_add_f32_e32 v152, v152, v210
	v_fma_f32 v214, v169, v213, v211
	v_cndmask_b32_e64 v169, v215, v214, s[38:39]
	ds_read_u16_d16_hi v148, v123 offset:25376
	ds_read_u16_d16_hi v149, v123 offset:25904
	ds_read_u16_d16_hi v150, v123 offset:26432
	ds_read_u16_d16_hi v151, v123 offset:26960
	v_min_f32_e32 v46, s20, v46
	v_min_f32_e32 v47, s20, v47
	v_min_f32_e32 v48, s20, v48
	v_min_f32_e32 v49, s20, v49
	v_min_f32_e32 v42, s20, v42
	v_min_f32_e32 v43, s20, v43
	v_min_f32_e32 v44, s20, v44
	v_min_f32_e32 v45, s20, v45
	v_exp_f32_e32 v46, v46
	v_exp_f32_e32 v47, v47
	v_exp_f32_e32 v48, v48
	v_exp_f32_e32 v49, v49
	v_exp_f32_e32 v42, v42
	v_exp_f32_e32 v43, v43
	v_exp_f32_e32 v44, v44
	v_exp_f32_e32 v45, v45
	v_pk_add_f32 v[46:47], v[46:47], 1.0 op_sel_hi:[1,0]
	v_pk_add_f32 v[48:49], v[48:49], 1.0 op_sel_hi:[1,0]
	v_pk_add_f32 v[42:43], v[42:43], 1.0 op_sel_hi:[1,0]
	v_pk_add_f32 v[44:45], v[44:45], 1.0 op_sel_hi:[1,0]
	v_pk_mul_f32 v[178:179], v[46:47], v[42:43]
	v_pk_mul_f32 v[180:181], v[48:49], v[44:45]
	v_rcp_f32_e32 v178, v178
	v_rcp_f32_e32 v179, v179
	v_rcp_f32_e32 v180, v180
	v_rcp_f32_e32 v181, v181
	v_pk_mul_f32 v[42:43], v[42:43], v[178:179]
	v_pk_mul_f32 v[44:45], v[44:45], v[180:181]
	v_pk_mul_f32 v[46:47], v[46:47], v[178:179]
	v_pk_mul_f32 v[48:49], v[48:49], v[180:181]
	v_pk_mul_f32 v[42:43], v[42:43], v[134:135] op_sel_hi:[1,0]
	v_pk_mul_f32 v[44:45], v[44:45], v[134:135] op_sel_hi:[1,0]
	v_cvt_pk_bf16_f32 v178, v42, v43
	v_cvt_pk_bf16_f32 v179, v44, v45
	v_lshlrev_b32_e32 v42, 16, v178
	v_lshlrev_b32_e32 v43, 16, v179
	v_and_b32_e32 v44, s21, v178
	v_and_b32_e32 v45, s21, v179
	v_exp_f32_e32 v184, v42
	v_exp_f32_e32 v185, v44
	v_exp_f32_e32 v186, v43
	v_exp_f32_e32 v187, v45
	s_waitcnt lgkmcnt(4)
	v_exp_f32_e32 v243, v240
	v_fma_f32 v245, v241, v242, v170
	v_add_f32_e32 v153, v153, v240
	v_fma_f32 v244, v170, v243, v241
	v_cndmask_b32_e64 v170, v245, v244, s[40:41]
	ds_bpermute_b32 v240, v130, v153
	v_exp_f32_e32 v242, v153
	ds_bpermute_b32 v241, v130, v170
	v_fma_f32 v180, -v184, v184, 1.0
	v_fma_f32 v181, -v185, v185, 1.0
	v_fma_f32 v182, -v186, v186, 1.0
	v_fma_f32 v183, -v187, v187, 1.0
	v_sqrt_f32_e64 v180, |v180|
	v_sqrt_f32_e64 v181, |v181|
	v_sqrt_f32_e64 v182, |v182|
	v_sqrt_f32_e64 v183, |v183|
	v_mov_b32_dpp v188, v178 quad_perm:[1,0,3,2] row_mask:0xf bank_mask:0xf bound_ctrl:1
	v_mov_b32_dpp v165, v179 quad_perm:[1,0,3,2] row_mask:0xf bank_mask:0xf bound_ctrl:1
	v_pk_mul_f32 v[180:181], v[180:181], v[46:47]
	v_pk_mul_f32 v[182:183], v[182:183], v[48:49]
	v_perm_b32 v206, v188, v178, v125
	v_perm_b32 v207, v165, v179, v125
	global_store_dword v126, v206, s[16:17] offset:32
	global_store_dword v127, v207, s[16:17] offset:32
	v_pk_mul_f32 v[180:181], v[180:181], v[144:145]
	v_pk_mul_f32 v[182:183], v[182:183], v[146:147]
	v_pk_add_f32 v[42:43], v[42:43], v[44:45]
	v_cvt_pk_bf16_f32 v46, v180, v181
	v_cvt_pk_bf16_f32 v47, v182, v183
	v_add_f32_e32 v154, v42, v43
	v_lshlrev_b32_e32 v180, 16, v46
	v_mov_b32_dpp v188, v46 quad_perm:[1,0,3,2] row_mask:0xf bank_mask:0xf bound_ctrl:1
	v_and_b32_e32 v181, s21, v46
	v_mov_b32_dpp v165, v47 quad_perm:[1,0,3,2] row_mask:0xf bank_mask:0xf bound_ctrl:1
	v_lshlrev_b32_e32 v182, 16, v47
	v_and_b32_e32 v183, s21, v47
	v_perm_b32 v208, v188, v46, v125
	v_perm_b32 v209, v165, v47, v125
	global_store_dword v126, v208, s[18:19] offset:32
	global_store_dword v127, v209, s[18:19] offset:32
	s_add_u32 s16, s16, 0x10000
	s_addc_u32 s17, s17, 0
	s_add_u32 s18, s18, 0x10000
	s_addc_u32 s19, s19, 0
	v_fma_f32 v214, v180, v185, v181
	v_fma_f32 v215, v183, v186, v182
	v_fma_f32 v214, v214, v186, v182
	v_fma_f32 v215, v215, v185, v181
	v_fma_f32 v214, v214, v187, v183
	v_fma_f32 v215, v215, v184, v180
	ds_bpermute_b32 v210, v129, v154
	v_cndmask_b32_e64 v171, v215, v214, s[30:31]
	v_exp_f32_e32 v212, v154
	ds_bpermute_b32 v211, v129, v171
	s_waitcnt lgkmcnt(2)
; #define LAS __attribute__((address_space(3)))
; __device__ __forceinline__ void p_rg_fused(const Frame& F0, const bf16* URAW, int L, const float* cw, const float* cbias, const bf16* Wg, const float* ba, const float* bx, const float* spt,
;                                            bf16* LA, bf16* INP, float* HEND, float* PROD) {
;     ...
;                 for (int m = 0; m < 8; ++m) {
;                     float lr[4], xr[4], ea[4]; unsigned lwv[4], xwv[4];
;                     int gq = g; asm volatile("" : "+v"(gq));
;                     {
;                         f32x4 u4;
; #pragma unroll
;                         for (int e = 0; e < 4; ++e) u4[e] = bf2f(*(const LAS bf16*)(ut + (16 * m + 4 * gq + e) * RGF_PITCH + cl * 2));
;                         const f32x4 na = acc[m][np], nb2 = acc[m][2 + np]; f32x4 e1, e2;
; #pragma unroll
;                         for (int e = 0; e < 4; ++e) { e1[e] = fexp2_(fminf(na[e], 115.f)); e2[e] = fexp2_(fminf(nb2[e], 115.f)); }
;                         const f32x4 d1 = e1 + 1.0f, d2 = e2 + 1.0f, dp = d1 * d2; f32x4 rc;
; #pragma unroll
;                         for (int e = 0; e < 4; ++e) rc[e] = frcp_(dp[e]);
;                         const f32x4 l4 = (d2 * rc) * psp, ig = d1 * rc;
;                         const unsigned lw01 = pk2(l4[0], l4[1]), lw23 = pk2(l4[2], l4[3]);
;                         lr[0] = bflo(lw01); lr[1] = bfhi(lw01); lr[2] = bflo(lw23); lr[3] = bfhi(lw23);
;                         f32x4 ea4, sq;
; #pragma unroll
;                         for (int e = 0; e < 4; ++e) { ea4[e] = fexp2_(lr[e]); ea[e] = ea4[e]; }
; #pragma unroll
;                         for (int e = 0; e < 4; ++e) sq[e] = fsqrt_(__builtin_fabsf(__builtin_fmaf(-ea4[e], ea4[e], 1.0f)));
;                         const f32x4 x4 = sq * ig * u4;
;                         const unsigned xw01 = pk2(x4[0], x4[1]), xw23 = pk2(x4[2], x4[3]);
;                         xr[0] = bflo(xw01); xr[1] = bfhi(xw01); xr[2] = bflo(xw23); xr[3] = bfhi(xw23);
;                         lwv[0] = lw01 & 0xffffu; lwv[1] = lw01 >> 16; lwv[2] = lw23 & 0xffffu; lwv[3] = lw23 >> 16;
;                         xwv[0] = xw01 & 0xffffu; xwv[1] = xw01 >> 16; xwv[2] = xw23 & 0xffffu; xwv[3] = xw23 >> 16; }
; #pragma unroll
;                     for (int ep = 0; ep < 2; ++ep) { const bool odd = (Lq & 1) != 0; const int tok = 16 * m + 4 * gq + 2 * ep + (odd ? 1 : 0);
	v_exp_f32_e32 v243, v240
	v_fma_f32 v245, v241, v242, v170
	v_add_f32_e32 v153, v153, v240
	v_fma_f32 v244, v170, v243, v241
	v_cndmask_b32_e64 v170, v245, v244, s[38:39]
	ds_read_u16_d16_hi v144, v123 offset:33824
	ds_read_u16_d16_hi v145, v123 offset:34352
	ds_read_u16_d16_hi v146, v123 offset:34880
	ds_read_u16_d16_hi v147, v123 offset:35408
	v_min_f32_e32 v38, s20, v38
	v_min_f32_e32 v39, s20, v39
	v_min_f32_e32 v40, s20, v40
	v_min_f32_e32 v41, s20, v41
	v_min_f32_e32 v34, s20, v34
	v_min_f32_e32 v35, s20, v35
	v_min_f32_e32 v36, s20, v36
	v_min_f32_e32 v37, s20, v37
	v_exp_f32_e32 v38, v38
	v_exp_f32_e32 v39, v39
	v_exp_f32_e32 v40, v40
	v_exp_f32_e32 v41, v41
	v_exp_f32_e32 v34, v34
	v_exp_f32_e32 v35, v35
	v_exp_f32_e32 v36, v36
	v_exp_f32_e32 v37, v37
	v_pk_add_f32 v[38:39], v[38:39], 1.0 op_sel_hi:[1,0]
	v_pk_add_f32 v[40:41], v[40:41], 1.0 op_sel_hi:[1,0]
	v_pk_add_f32 v[34:35], v[34:35], 1.0 op_sel_hi:[1,0]
	v_pk_add_f32 v[36:37], v[36:37], 1.0 op_sel_hi:[1,0]
	v_pk_mul_f32 v[216:217], v[38:39], v[34:35]
	v_pk_mul_f32 v[218:219], v[40:41], v[36:37]
	v_rcp_f32_e32 v216, v216
	v_rcp_f32_e32 v217, v217
	v_rcp_f32_e32 v218, v218
	v_rcp_f32_e32 v219, v219
	v_pk_mul_f32 v[34:35], v[34:35], v[216:217]
	v_pk_mul_f32 v[36:37], v[36:37], v[218:219]
	v_pk_mul_f32 v[38:39], v[38:39], v[216:217]
	v_pk_mul_f32 v[40:41], v[40:41], v[218:219]
	v_pk_mul_f32 v[34:35], v[34:35], v[134:135] op_sel_hi:[1,0]
	v_pk_mul_f32 v[36:37], v[36:37], v[134:135] op_sel_hi:[1,0]
	v_cvt_pk_bf16_f32 v216, v34, v35
	v_cvt_pk_bf16_f32 v217, v36, v37
	v_lshlrev_b32_e32 v34, 16, v216
	v_lshlrev_b32_e32 v35, 16, v217
	v_and_b32_e32 v36, s21, v216
	v_and_b32_e32 v37, s21, v217
	v_exp_f32_e32 v222, v34
	v_exp_f32_e32 v223, v36
	v_exp_f32_e32 v224, v35
	v_exp_f32_e32 v225, v37
	s_waitcnt lgkmcnt(4)
	v_exp_f32_e32 v213, v210
	v_fma_f32 v215, v211, v212, v171
	v_add_f32_e32 v154, v154, v210
	v_fma_f32 v214, v171, v213, v211
	v_cndmask_b32_e64 v171, v215, v214, s[40:41]
	ds_bpermute_b32 v210, v130, v154
	v_exp_f32_e32 v212, v154
	ds_bpermute_b32 v211, v130, v171
	v_fma_f32 v218, -v222, v222, 1.0
	v_fma_f32 v219, -v223, v223, 1.0
	v_fma_f32 v220, -v224, v224, 1.0
	v_fma_f32 v221, -v225, v225, 1.0
	v_sqrt_f32_e64 v218, |v218|
	v_sqrt_f32_e64 v219, |v219|
	v_sqrt_f32_e64 v220, |v220|
	v_sqrt_f32_e64 v221, |v221|
	v_mov_b32_dpp v166, v216 quad_perm:[1,0,3,2] row_mask:0xf bank_mask:0xf bound_ctrl:1
	v_mov_b32_dpp v167, v217 quad_perm:[1,0,3,2] row_mask:0xf bank_mask:0xf bound_ctrl:1
	v_pk_mul_f32 v[218:219], v[218:219], v[38:39]
	v_pk_mul_f32 v[220:221], v[220:221], v[40:41]
	v_perm_b32 v236, v166, v216, v125
	v_perm_b32 v237, v167, v217, v125
	global_store_dword v126, v236, s[16:17] offset:32
	global_store_dword v127, v237, s[16:17] offset:32
	v_pk_mul_f32 v[218:219], v[218:219], v[148:149]
	v_pk_mul_f32 v[220:221], v[220:221], v[150:151]
	v_pk_add_f32 v[34:35], v[34:35], v[36:37]
	v_cvt_pk_bf16_f32 v38, v218, v219
	v_cvt_pk_bf16_f32 v39, v220, v221
	v_add_f32_e32 v155, v34, v35
	v_lshlrev_b32_e32 v218, 16, v38
	v_mov_b32_dpp v166, v38 quad_perm:[1,0,3,2] row_mask:0xf bank_mask:0xf bound_ctrl:1
	v_and_b32_e32 v219, s21, v38
	v_mov_b32_dpp v167, v39 quad_perm:[1,0,3,2] row_mask:0xf bank_mask:0xf bound_ctrl:1
	v_lshlrev_b32_e32 v220, 16, v39
	v_and_b32_e32 v221, s21, v39
	v_perm_b32 v238, v166, v38, v125
	v_perm_b32 v239, v167, v39, v125
	global_store_dword v126, v238, s[18:19] offset:32
	global_store_dword v127, v239, s[18:19] offset:32
	s_add_u32 s16, s16, 0x10000
	s_addc_u32 s17, s17, 0
	s_add_u32 s18, s18, 0x10000
	s_addc_u32 s19, s19, 0
	v_fma_f32 v244, v218, v223, v219
	v_fma_f32 v245, v221, v224, v220
	v_fma_f32 v244, v244, v224, v220
	v_fma_f32 v245, v245, v223, v219
	v_fma_f32 v244, v244, v225, v221
	v_fma_f32 v245, v245, v222, v218
	ds_bpermute_b32 v240, v129, v155
	v_cndmask_b32_e64 v172, v245, v244, s[30:31]
	v_exp_f32_e32 v242, v155
	ds_bpermute_b32 v241, v129, v172
	s_waitcnt lgkmcnt(2)
	v_exp_f32_e32 v213, v210
	v_fma_f32 v215, v211, v212, v171
	v_add_f32_e32 v154, v154, v210
	v_fma_f32 v214, v171, v213, v211
	v_cndmask_b32_e64 v171, v215, v214, s[38:39]
	ds_read_u16_d16_hi v148, v123 offset:42272
	ds_read_u16_d16_hi v149, v123 offset:42800
	ds_read_u16_d16_hi v150, v123 offset:43328
	ds_read_u16_d16_hi v151, v123 offset:43856
	v_min_f32_e32 v30, s20, v30
	v_min_f32_e32 v31, s20, v31
	v_min_f32_e32 v32, s20, v32
	v_min_f32_e32 v33, s20, v33
	v_min_f32_e32 v26, s20, v26
	v_min_f32_e32 v27, s20, v27
	v_min_f32_e32 v28, s20, v28
	v_min_f32_e32 v29, s20, v29
	v_exp_f32_e32 v30, v30
	v_exp_f32_e32 v31, v31
	v_exp_f32_e32 v32, v32
	v_exp_f32_e32 v33, v33
	v_exp_f32_e32 v26, v26
	v_exp_f32_e32 v27, v27
	v_exp_f32_e32 v28, v28
	v_exp_f32_e32 v29, v29
	v_pk_add_f32 v[30:31], v[30:31], 1.0 op_sel_hi:[1,0]
	v_pk_add_f32 v[32:33], v[32:33], 1.0 op_sel_hi:[1,0]
	v_pk_add_f32 v[26:27], v[26:27], 1.0 op_sel_hi:[1,0]
	v_pk_add_f32 v[28:29], v[28:29], 1.0 op_sel_hi:[1,0]
	v_pk_mul_f32 v[178:179], v[30:31], v[26:27]
	v_pk_mul_f32 v[180:181], v[32:33], v[28:29]
	v_rcp_f32_e32 v178, v178
	v_rcp_f32_e32 v179, v179
	v_rcp_f32_e32 v180, v180
	v_rcp_f32_e32 v181, v181
	v_pk_mul_f32 v[26:27], v[26:27], v[178:179]
	v_pk_mul_f32 v[28:29], v[28:29], v[180:181]
	v_pk_mul_f32 v[30:31], v[30:31], v[178:179]
	v_pk_mul_f32 v[32:33], v[32:33], v[180:181]
	v_pk_mul_f32 v[26:27], v[26:27], v[134:135] op_sel_hi:[1,0]
	v_pk_mul_f32 v[28:29], v[28:29], v[134:135] op_sel_hi:[1,0]
	v_cvt_pk_bf16_f32 v178, v26, v27
	v_cvt_pk_bf16_f32 v179, v28, v29
	v_lshlrev_b32_e32 v26, 16, v178
	v_lshlrev_b32_e32 v27, 16, v179
	v_and_b32_e32 v28, s21, v178
	v_and_b32_e32 v29, s21, v179
	v_exp_f32_e32 v184, v26
	v_exp_f32_e32 v185, v28
	v_exp_f32_e32 v186, v27
	v_exp_f32_e32 v187, v29
	s_waitcnt lgkmcnt(4)
; #define LAS __attribute__((address_space(3)))
; __device__ __forceinline__ void p_rg_fused(const Frame& F0, const bf16* URAW, int L, const float* cw, const float* cbias, const bf16* Wg, const float* ba, const float* bx, const float* spt,
;                                            bf16* LA, bf16* INP, float* HEND, float* PROD) {
;     ...
;                 for (int m = 0; m < 8; ++m) {
;                     float lr[4], xr[4], ea[4]; unsigned lwv[4], xwv[4];
;                     int gq = g; asm volatile("" : "+v"(gq));
;                     {
;                         f32x4 u4;
; #pragma unroll
;                         for (int e = 0; e < 4; ++e) u4[e] = bf2f(*(const LAS bf16*)(ut + (16 * m + 4 * gq + e) * RGF_PITCH + cl * 2));
;                         const f32x4 na = acc[m][np], nb2 = acc[m][2 + np]; f32x4 e1, e2;
; #pragma unroll
;                         for (int e = 0; e < 4; ++e) { e1[e] = fexp2_(fminf(na[e], 115.f)); e2[e] = fexp2_(fminf(nb2[e], 115.f)); }
;                         const f32x4 d1 = e1 + 1.0f, d2 = e2 + 1.0f, dp = d1 * d2; f32x4 rc;
; #pragma unroll
;                         for (int e = 0; e < 4; ++e) rc[e] = frcp_(dp[e]);
;                         const f32x4 l4 = (d2 * rc) * psp, ig = d1 * rc;
;                         const unsigned lw01 = pk2(l4[0], l4[1]), lw23 = pk2(l4[2], l4[3]);
;                         lr[0] = bflo(lw01); lr[1] = bfhi(lw01); lr[2] = bflo(lw23); lr[3] = bfhi(lw23);
;                         f32x4 ea4, sq;
; #pragma unroll
;                         for (int e = 0; e < 4; ++e) { ea4[e] = fexp2_(lr[e]); ea[e] = ea4[e]; }
; #pragma unroll
;                         for (int e = 0; e < 4; ++e) sq[e] = fsqrt_(__builtin_fabsf(__builtin_fmaf(-ea4[e], ea4[e], 1.0f)));
;                         const f32x4 x4 = sq * ig * u4;
;                         const unsigned xw01 = pk2(x4[0], x4[1]), xw23 = pk2(x4[2], x4[3]);
;                         xr[0] = bflo(xw01); xr[1] = bfhi(xw01); xr[2] = bflo(xw23); xr[3] = bfhi(xw23);
;                         lwv[0] = lw01 & 0xffffu; lwv[1] = lw01 >> 16; lwv[2] = lw23 & 0xffffu; lwv[3] = lw23 >> 16;
;                         xwv[0] = xw01 & 0xffffu; xwv[1] = xw01 >> 16; xwv[2] = xw23 & 0xffffu; xwv[3] = xw23 >> 16; }
; #pragma unroll
;                     for (int ep = 0; ep < 2; ++ep) { const bool odd = (Lq & 1) != 0; const int tok = 16 * m + 4 * gq + 2 * ep + (odd ? 1 : 0);
	v_exp_f32_e32 v243, v240
	v_fma_f32 v245, v241, v242, v172
	v_add_f32_e32 v155, v155, v240
	v_fma_f32 v244, v172, v243, v241
	v_cndmask_b32_e64 v172, v245, v244, s[40:41]
	ds_bpermute_b32 v240, v130, v155
	v_exp_f32_e32 v242, v155
	ds_bpermute_b32 v241, v130, v172
	v_fma_f32 v180, -v184, v184, 1.0
	v_fma_f32 v181, -v185, v185, 1.0
	v_fma_f32 v182, -v186, v186, 1.0
	v_fma_f32 v183, -v187, v187, 1.0
	v_sqrt_f32_e64 v180, |v180|
	v_sqrt_f32_e64 v181, |v181|
	v_sqrt_f32_e64 v182, |v182|
	v_sqrt_f32_e64 v183, |v183|
	v_mov_b32_dpp v188, v178 quad_perm:[1,0,3,2] row_mask:0xf bank_mask:0xf bound_ctrl:1
	v_mov_b32_dpp v165, v179 quad_perm:[1,0,3,2] row_mask:0xf bank_mask:0xf bound_ctrl:1
	v_pk_mul_f32 v[180:181], v[180:181], v[30:31]
	v_pk_mul_f32 v[182:183], v[182:183], v[32:33]
	v_perm_b32 v206, v188, v178, v125
	v_perm_b32 v207, v165, v179, v125
	global_store_dword v126, v206, s[16:17] offset:32
	global_store_dword v127, v207, s[16:17] offset:32
	v_pk_mul_f32 v[180:181], v[180:181], v[144:145]
	v_pk_mul_f32 v[182:183], v[182:183], v[146:147]
	v_pk_add_f32 v[26:27], v[26:27], v[28:29]
	v_cvt_pk_bf16_f32 v30, v180, v181
	v_cvt_pk_bf16_f32 v31, v182, v183
	v_add_f32_e32 v156, v26, v27
	v_lshlrev_b32_e32 v180, 16, v30
	v_mov_b32_dpp v188, v30 quad_perm:[1,0,3,2] row_mask:0xf bank_mask:0xf bound_ctrl:1
	v_and_b32_e32 v181, s21, v30
	v_mov_b32_dpp v165, v31 quad_perm:[1,0,3,2] row_mask:0xf bank_mask:0xf bound_ctrl:1
	v_lshlrev_b32_e32 v182, 16, v31
	v_and_b32_e32 v183, s21, v31
	v_perm_b32 v208, v188, v30, v125
	v_perm_b32 v209, v165, v31, v125
	global_store_dword v126, v208, s[18:19] offset:32
	global_store_dword v127, v209, s[18:19] offset:32
	s_add_u32 s16, s16, 0x10000
	s_addc_u32 s17, s17, 0
	s_add_u32 s18, s18, 0x10000
	s_addc_u32 s19, s19, 0
	v_fma_f32 v214, v180, v185, v181
	v_fma_f32 v215, v183, v186, v182
	v_fma_f32 v214, v214, v186, v182
	v_fma_f32 v215, v215, v185, v181
	v_fma_f32 v214, v214, v187, v183
	v_fma_f32 v215, v215, v184, v180
	ds_bpermute_b32 v210, v129, v156
	v_cndmask_b32_e64 v173, v215, v214, s[30:31]
	v_exp_f32_e32 v212, v156
	ds_bpermute_b32 v211, v129, v173
	s_waitcnt lgkmcnt(2)
	v_exp_f32_e32 v243, v240
	v_fma_f32 v245, v241, v242, v172
	v_add_f32_e32 v155, v155, v240
	v_fma_f32 v244, v172, v243, v241
	v_cndmask_b32_e64 v172, v245, v244, s[38:39]
	ds_read_u16_d16_hi v144, v123 offset:50720
	ds_read_u16_d16_hi v145, v123 offset:51248
	ds_read_u16_d16_hi v146, v123 offset:51776
	ds_read_u16_d16_hi v147, v123 offset:52304
	v_min_f32_e32 v22, s20, v22
	v_min_f32_e32 v23, s20, v23
	v_min_f32_e32 v24, s20, v24
	v_min_f32_e32 v25, s20, v25
	v_min_f32_e32 v18, s20, v18
	v_min_f32_e32 v19, s20, v19
	v_min_f32_e32 v20, s20, v20
	v_min_f32_e32 v21, s20, v21
	v_exp_f32_e32 v22, v22
	v_exp_f32_e32 v23, v23
	v_exp_f32_e32 v24, v24
	v_exp_f32_e32 v25, v25
	v_exp_f32_e32 v18, v18
	v_exp_f32_e32 v19, v19
	v_exp_f32_e32 v20, v20
	v_exp_f32_e32 v21, v21
	v_pk_add_f32 v[22:23], v[22:23], 1.0 op_sel_hi:[1,0]
	v_pk_add_f32 v[24:25], v[24:25], 1.0 op_sel_hi:[1,0]
	v_pk_add_f32 v[18:19], v[18:19], 1.0 op_sel_hi:[1,0]
	v_pk_add_f32 v[20:21], v[20:21], 1.0 op_sel_hi:[1,0]
	v_pk_mul_f32 v[216:217], v[22:23], v[18:19]
	v_pk_mul_f32 v[218:219], v[24:25], v[20:21]
	v_rcp_f32_e32 v216, v216
	v_rcp_f32_e32 v217, v217
	v_rcp_f32_e32 v218, v218
	v_rcp_f32_e32 v219, v219
	v_pk_mul_f32 v[18:19], v[18:19], v[216:217]
	v_pk_mul_f32 v[20:21], v[20:21], v[218:219]
	v_pk_mul_f32 v[22:23], v[22:23], v[216:217]
	v_pk_mul_f32 v[24:25], v[24:25], v[218:219]
	v_pk_mul_f32 v[18:19], v[18:19], v[134:135] op_sel_hi:[1,0]
	v_pk_mul_f32 v[20:21], v[20:21], v[134:135] op_sel_hi:[1,0]
	v_cvt_pk_bf16_f32 v216, v18, v19
	v_cvt_pk_bf16_f32 v217, v20, v21
	v_lshlrev_b32_e32 v18, 16, v216
	v_lshlrev_b32_e32 v19, 16, v217
	v_and_b32_e32 v20, s21, v216
	v_and_b32_e32 v21, s21, v217
	v_exp_f32_e32 v222, v18
	v_exp_f32_e32 v223, v20
	v_exp_f32_e32 v224, v19
	v_exp_f32_e32 v225, v21
	s_waitcnt lgkmcnt(4)
	v_exp_f32_e32 v213, v210
	v_fma_f32 v215, v211, v212, v173
	v_add_f32_e32 v156, v156, v210
	v_fma_f32 v214, v173, v213, v211
	v_cndmask_b32_e64 v173, v215, v214, s[40:41]
	ds_bpermute_b32 v210, v130, v156
	v_exp_f32_e32 v212, v156
	ds_bpermute_b32 v211, v130, v173
	v_fma_f32 v218, -v222, v222, 1.0
	v_fma_f32 v219, -v223, v223, 1.0
	v_fma_f32 v220, -v224, v224, 1.0
	v_fma_f32 v221, -v225, v225, 1.0
	v_sqrt_f32_e64 v218, |v218|
	v_sqrt_f32_e64 v219, |v219|
	v_sqrt_f32_e64 v220, |v220|
	v_sqrt_f32_e64 v221, |v221|
	v_mov_b32_dpp v166, v216 quad_perm:[1,0,3,2] row_mask:0xf bank_mask:0xf bound_ctrl:1
	v_mov_b32_dpp v167, v217 quad_perm:[1,0,3,2] row_mask:0xf bank_mask:0xf bound_ctrl:1
	v_pk_mul_f32 v[218:219], v[218:219], v[22:23]
	v_pk_mul_f32 v[220:221], v[220:221], v[24:25]
	v_perm_b32 v236, v166, v216, v125
	v_perm_b32 v237, v167, v217, v125
	global_store_dword v126, v236, s[16:17] offset:32
	global_store_dword v127, v237, s[16:17] offset:32
	v_pk_mul_f32 v[218:219], v[218:219], v[148:149]
	v_pk_mul_f32 v[220:221], v[220:221], v[150:151]
	v_pk_add_f32 v[18:19], v[18:19], v[20:21]
	v_cvt_pk_bf16_f32 v22, v218, v219
	v_cvt_pk_bf16_f32 v23, v220, v221
	v_add_f32_e32 v157, v18, v19
	v_lshlrev_b32_e32 v218, 16, v22
	v_mov_b32_dpp v166, v22 quad_perm:[1,0,3,2] row_mask:0xf bank_mask:0xf bound_ctrl:1
	v_and_b32_e32 v219, s21, v22
	v_mov_b32_dpp v167, v23 quad_perm:[1,0,3,2] row_mask:0xf bank_mask:0xf bound_ctrl:1
	v_lshlrev_b32_e32 v220, 16, v23
	v_and_b32_e32 v221, s21, v23
	v_perm_b32 v238, v166, v22, v125
	v_perm_b32 v239, v167, v23, v125
	global_store_dword v126, v238, s[18:19] offset:32
	global_store_dword v127, v239, s[18:19] offset:32
	s_add_u32 s16, s16, 0x10000
	s_addc_u32 s17, s17, 0
	s_add_u32 s18, s18, 0x10000
	s_addc_u32 s19, s19, 0
	v_fma_f32 v244, v218, v223, v219
	v_fma_f32 v245, v221, v224, v220
	v_fma_f32 v244, v244, v224, v220
	v_fma_f32 v245, v245, v223, v219
	v_fma_f32 v244, v244, v225, v221
	v_fma_f32 v245, v245, v222, v218
	ds_bpermute_b32 v240, v129, v157
	v_cndmask_b32_e64 v174, v245, v244, s[30:31]
	v_exp_f32_e32 v242, v157
	ds_bpermute_b32 v241, v129, v174
	s_waitcnt lgkmcnt(2)
; #define LAS __attribute__((address_space(3)))
; __device__ __forceinline__ void p_rg_fused(const Frame& F0, const bf16* URAW, int L, const float* cw, const float* cbias, const bf16* Wg, const float* ba, const float* bx, const float* spt,
;                                            bf16* LA, bf16* INP, float* HEND, float* PROD) {
;     ...
;                 for (int m = 0; m < 8; ++m) {
;                     float lr[4], xr[4], ea[4]; unsigned lwv[4], xwv[4];
;                     int gq = g; asm volatile("" : "+v"(gq));
;                     {
;                         f32x4 u4;
; #pragma unroll
;                         for (int e = 0; e < 4; ++e) u4[e] = bf2f(*(const LAS bf16*)(ut + (16 * m + 4 * gq + e) * RGF_PITCH + cl * 2));
;                         const f32x4 na = acc[m][np], nb2 = acc[m][2 + np]; f32x4 e1, e2;
; #pragma unroll
;                         for (int e = 0; e < 4; ++e) { e1[e] = fexp2_(fminf(na[e], 115.f)); e2[e] = fexp2_(fminf(nb2[e], 115.f)); }
;                         const f32x4 d1 = e1 + 1.0f, d2 = e2 + 1.0f, dp = d1 * d2; f32x4 rc;
; #pragma unroll
;                         for (int e = 0; e < 4; ++e) rc[e] = frcp_(dp[e]);
;                         const f32x4 l4 = (d2 * rc) * psp, ig = d1 * rc;
;                         const unsigned lw01 = pk2(l4[0], l4[1]), lw23 = pk2(l4[2], l4[3]);
;                         lr[0] = bflo(lw01); lr[1] = bfhi(lw01); lr[2] = bflo(lw23); lr[3] = bfhi(lw23);
;                         f32x4 ea4, sq;
; #pragma unroll
;                         for (int e = 0; e < 4; ++e) { ea4[e] = fexp2_(lr[e]); ea[e] = ea4[e]; }
; #pragma unroll
;                         for (int e = 0; e < 4; ++e) sq[e] = fsqrt_(__builtin_fabsf(__builtin_fmaf(-ea4[e], ea4[e], 1.0f)));
;                         const f32x4 x4 = sq * ig * u4;
;                         const unsigned xw01 = pk2(x4[0], x4[1]), xw23 = pk2(x4[2], x4[3]);
;                         xr[0] = bflo(xw01); xr[1] = bfhi(xw01); xr[2] = bflo(xw23); xr[3] = bfhi(xw23);
;                         lwv[0] = lw01 & 0xffffu; lwv[1] = lw01 >> 16; lwv[2] = lw23 & 0xffffu; lwv[3] = lw23 >> 16;
;                         xwv[0] = xw01 & 0xffffu; xwv[1] = xw01 >> 16; xwv[2] = xw23 & 0xffffu; xwv[3] = xw23 >> 16; }
; #pragma unroll
;                     for (int ep = 0; ep < 2; ++ep) { const bool odd = (Lq & 1) != 0; const int tok = 16 * m + 4 * gq + 2 * ep + (odd ? 1 : 0);
	v_exp_f32_e32 v213, v210
	v_fma_f32 v215, v211, v212, v173
	v_add_f32_e32 v156, v156, v210
	v_fma_f32 v214, v173, v213, v211
	v_cndmask_b32_e64 v173, v215, v214, s[38:39]
	ds_read_u16_d16_hi v148, v123 offset:59168
	ds_read_u16_d16_hi v149, v123 offset:59696
	ds_read_u16_d16_hi v150, v123 offset:60224
	ds_read_u16_d16_hi v151, v123 offset:60752
	v_min_f32_e32 v14, s20, v14
	v_min_f32_e32 v15, s20, v15
	v_min_f32_e32 v16, s20, v16
	v_min_f32_e32 v17, s20, v17
	v_min_f32_e32 v10, s20, v10
	v_min_f32_e32 v11, s20, v11
	v_min_f32_e32 v12, s20, v12
	v_min_f32_e32 v13, s20, v13
	v_exp_f32_e32 v14, v14
	v_exp_f32_e32 v15, v15
	v_exp_f32_e32 v16, v16
	v_exp_f32_e32 v17, v17
	v_exp_f32_e32 v10, v10
	v_exp_f32_e32 v11, v11
	v_exp_f32_e32 v12, v12
	v_exp_f32_e32 v13, v13
	v_pk_add_f32 v[14:15], v[14:15], 1.0 op_sel_hi:[1,0]
	v_pk_add_f32 v[16:17], v[16:17], 1.0 op_sel_hi:[1,0]
	v_pk_add_f32 v[10:11], v[10:11], 1.0 op_sel_hi:[1,0]
	v_pk_add_f32 v[12:13], v[12:13], 1.0 op_sel_hi:[1,0]
	v_pk_mul_f32 v[178:179], v[14:15], v[10:11]
	v_pk_mul_f32 v[180:181], v[16:17], v[12:13]
	v_rcp_f32_e32 v178, v178
	v_rcp_f32_e32 v179, v179
	v_rcp_f32_e32 v180, v180
	v_rcp_f32_e32 v181, v181
	v_pk_mul_f32 v[10:11], v[10:11], v[178:179]
	v_pk_mul_f32 v[12:13], v[12:13], v[180:181]
	v_pk_mul_f32 v[14:15], v[14:15], v[178:179]
	v_pk_mul_f32 v[16:17], v[16:17], v[180:181]
	v_pk_mul_f32 v[10:11], v[10:11], v[134:135] op_sel_hi:[1,0]
	v_pk_mul_f32 v[12:13], v[12:13], v[134:135] op_sel_hi:[1,0]
	v_cvt_pk_bf16_f32 v178, v10, v11
	v_cvt_pk_bf16_f32 v179, v12, v13
	v_lshlrev_b32_e32 v10, 16, v178
	v_lshlrev_b32_e32 v11, 16, v179
	v_and_b32_e32 v12, s21, v178
	v_and_b32_e32 v13, s21, v179
	v_exp_f32_e32 v184, v10
	v_exp_f32_e32 v185, v12
	v_exp_f32_e32 v186, v11
	v_exp_f32_e32 v187, v13
	s_waitcnt lgkmcnt(4)
	v_exp_f32_e32 v243, v240
	v_fma_f32 v245, v241, v242, v174
	v_add_f32_e32 v157, v157, v240
	v_fma_f32 v244, v174, v243, v241
	v_cndmask_b32_e64 v174, v245, v244, s[40:41]
	ds_bpermute_b32 v240, v130, v157
	v_exp_f32_e32 v242, v157
	ds_bpermute_b32 v241, v130, v174
	v_fma_f32 v180, -v184, v184, 1.0
	v_fma_f32 v181, -v185, v185, 1.0
	v_fma_f32 v182, -v186, v186, 1.0
	v_fma_f32 v183, -v187, v187, 1.0
	v_sqrt_f32_e64 v180, |v180|
	v_sqrt_f32_e64 v181, |v181|
	v_sqrt_f32_e64 v182, |v182|
	v_sqrt_f32_e64 v183, |v183|
	v_mov_b32_dpp v188, v178 quad_perm:[1,0,3,2] row_mask:0xf bank_mask:0xf bound_ctrl:1
	v_mov_b32_dpp v165, v179 quad_perm:[1,0,3,2] row_mask:0xf bank_mask:0xf bound_ctrl:1
	v_pk_mul_f32 v[180:181], v[180:181], v[14:15]
	v_pk_mul_f32 v[182:183], v[182:183], v[16:17]
	v_perm_b32 v206, v188, v178, v125
	v_perm_b32 v207, v165, v179, v125
	global_store_dword v126, v206, s[16:17] offset:32
	global_store_dword v127, v207, s[16:17] offset:32
	v_pk_mul_f32 v[180:181], v[180:181], v[144:145]
	v_pk_mul_f32 v[182:183], v[182:183], v[146:147]
	v_pk_add_f32 v[10:11], v[10:11], v[12:13]
	v_cvt_pk_bf16_f32 v14, v180, v181
	v_cvt_pk_bf16_f32 v15, v182, v183
	v_add_f32_e32 v158, v10, v11
	v_lshlrev_b32_e32 v180, 16, v14
	v_mov_b32_dpp v188, v14 quad_perm:[1,0,3,2] row_mask:0xf bank_mask:0xf bound_ctrl:1
	v_and_b32_e32 v181, s21, v14
	v_mov_b32_dpp v165, v15 quad_perm:[1,0,3,2] row_mask:0xf bank_mask:0xf bound_ctrl:1
	v_lshlrev_b32_e32 v182, 16, v15
	v_and_b32_e32 v183, s21, v15
	v_perm_b32 v208, v188, v14, v125
	v_perm_b32 v209, v165, v15, v125
	global_store_dword v126, v208, s[18:19] offset:32
	global_store_dword v127, v209, s[18:19] offset:32
	s_add_u32 s16, s16, 0x10000
	s_addc_u32 s17, s17, 0
	s_add_u32 s18, s18, 0x10000
	s_addc_u32 s19, s19, 0
	v_fma_f32 v214, v180, v185, v181
	v_fma_f32 v215, v183, v186, v182
	v_fma_f32 v214, v214, v186, v182
	v_fma_f32 v215, v215, v185, v181
	v_fma_f32 v214, v214, v187, v183
	v_fma_f32 v215, v215, v184, v180
	ds_bpermute_b32 v210, v129, v158
	v_cndmask_b32_e64 v175, v215, v214, s[30:31]
	v_exp_f32_e32 v212, v158
	ds_bpermute_b32 v211, v129, v175
	s_waitcnt lgkmcnt(2)
; #define LAS __attribute__((address_space(3)))
; __device__ __forceinline__ void p_rg_fused(const Frame& F0, const bf16* URAW, int L, const float* cw, const float* cbias, const bf16* Wg, const float* ba, const float* bx, const float* spt,
;                                            bf16* LA, bf16* INP, float* HEND, float* PROD) {
;     ...
;                 for (int m = 0; m < 8; ++m) {
;                     float lr[4], xr[4], ea[4]; unsigned lwv[4], xwv[4];
;                     int gq = g; asm volatile("" : "+v"(gq));
;                     {
;                         f32x4 u4;
; #pragma unroll
;                         for (int e = 0; e < 4; ++e) u4[e] = bf2f(*(const LAS bf16*)(ut + (16 * m + 4 * gq + e) * RGF_PITCH + cl * 2));
;                         const f32x4 na = acc[m][np], nb2 = acc[m][2 + np]; f32x4 e1, e2;
; #pragma unroll
;                         for (int e = 0; e < 4; ++e) { e1[e] = fexp2_(fminf(na[e], 115.f)); e2[e] = fexp2_(fminf(nb2[e], 115.f)); }
;                         const f32x4 d1 = e1 + 1.0f, d2 = e2 + 1.0f, dp = d1 * d2; f32x4 rc;
; #pragma unroll
;                         for (int e = 0; e < 4; ++e) rc[e] = frcp_(dp[e]);
;                         const f32x4 l4 = (d2 * rc) * psp, ig = d1 * rc;
;                         const unsigned lw01 = pk2(l4[0], l4[1]), lw23 = pk2(l4[2], l4[3]);
;                         lr[0] = bflo(lw01); lr[1] = bfhi(lw01); lr[2] = bflo(lw23); lr[3] = bfhi(lw23);
;                         f32x4 ea4, sq;
; #pragma unroll
;                         for (int e = 0; e < 4; ++e) { ea4[e] = fexp2_(lr[e]); ea[e] = ea4[e]; }
; #pragma unroll
;                         for (int e = 0; e < 4; ++e) sq[e] = fsqrt_(__builtin_fabsf(__builtin_fmaf(-ea4[e], ea4[e], 1.0f)));
;                         const f32x4 x4 = sq * ig * u4;
;                         const unsigned xw01 = pk2(x4[0], x4[1]), xw23 = pk2(x4[2], x4[3]);
;                         xr[0] = bflo(xw01); xr[1] = bfhi(xw01); xr[2] = bflo(xw23); xr[3] = bfhi(xw23);
;                         lwv[0] = lw01 & 0xffffu; lwv[1] = lw01 >> 16; lwv[2] = lw23 & 0xffffu; lwv[3] = lw23 >> 16;
;                         xwv[0] = xw01 & 0xffffu; xwv[1] = xw01 >> 16; xwv[2] = xw23 & 0xffffu; xwv[3] = xw23 >> 16; }
; #pragma unroll
;                     for (int ep = 0; ep < 2; ++ep) { const bool odd = (Lq & 1) != 0; const int tok = 16 * m + 4 * gq + 2 * ep + (odd ? 1 : 0);
	v_exp_f32_e32 v243, v240
	v_fma_f32 v245, v241, v242, v174
	v_add_f32_e32 v157, v157, v240
	v_fma_f32 v244, v174, v243, v241
	v_cndmask_b32_e64 v174, v245, v244, s[38:39]
	v_min_f32_e32 v6, s20, v6
	v_min_f32_e32 v7, s20, v7
	v_min_f32_e32 v8, s20, v8
	v_min_f32_e32 v9, s20, v9
	v_min_f32_e32 v2, s20, v2
	v_min_f32_e32 v3, s20, v3
	v_min_f32_e32 v4, s20, v4
	v_min_f32_e32 v5, s20, v5
	v_exp_f32_e32 v6, v6
	v_exp_f32_e32 v7, v7
	v_exp_f32_e32 v8, v8
	v_exp_f32_e32 v9, v9
	v_exp_f32_e32 v2, v2
	v_exp_f32_e32 v3, v3
	v_exp_f32_e32 v4, v4
	v_exp_f32_e32 v5, v5
	v_pk_add_f32 v[6:7], v[6:7], 1.0 op_sel_hi:[1,0]
	v_pk_add_f32 v[8:9], v[8:9], 1.0 op_sel_hi:[1,0]
	v_pk_add_f32 v[2:3], v[2:3], 1.0 op_sel_hi:[1,0]
	v_pk_add_f32 v[4:5], v[4:5], 1.0 op_sel_hi:[1,0]
	v_pk_mul_f32 v[216:217], v[6:7], v[2:3]
	v_pk_mul_f32 v[218:219], v[8:9], v[4:5]
	v_rcp_f32_e32 v216, v216
	v_rcp_f32_e32 v217, v217
	v_rcp_f32_e32 v218, v218
	v_rcp_f32_e32 v219, v219
	v_pk_mul_f32 v[2:3], v[2:3], v[216:217]
	v_pk_mul_f32 v[4:5], v[4:5], v[218:219]
	v_pk_mul_f32 v[6:7], v[6:7], v[216:217]
	v_pk_mul_f32 v[8:9], v[8:9], v[218:219]
	v_pk_mul_f32 v[2:3], v[2:3], v[134:135] op_sel_hi:[1,0]
	v_pk_mul_f32 v[4:5], v[4:5], v[134:135] op_sel_hi:[1,0]
	v_cvt_pk_bf16_f32 v216, v2, v3
	v_cvt_pk_bf16_f32 v217, v4, v5
	v_lshlrev_b32_e32 v2, 16, v216
	v_lshlrev_b32_e32 v3, 16, v217
	v_and_b32_e32 v4, s21, v216
	v_and_b32_e32 v5, s21, v217
	v_exp_f32_e32 v222, v2
	v_exp_f32_e32 v223, v4
	v_exp_f32_e32 v224, v3
	v_exp_f32_e32 v225, v5
	s_waitcnt lgkmcnt(0)
	v_exp_f32_e32 v213, v210
	v_fma_f32 v215, v211, v212, v175
	v_add_f32_e32 v158, v158, v210
	v_fma_f32 v214, v175, v213, v211
	v_cndmask_b32_e64 v175, v215, v214, s[40:41]
	ds_bpermute_b32 v210, v130, v158
	v_exp_f32_e32 v212, v158
	ds_bpermute_b32 v211, v130, v175
	v_fma_f32 v218, -v222, v222, 1.0
	v_fma_f32 v219, -v223, v223, 1.0
	v_fma_f32 v220, -v224, v224, 1.0
	v_fma_f32 v221, -v225, v225, 1.0
	v_sqrt_f32_e64 v218, |v218|
	v_sqrt_f32_e64 v219, |v219|
	v_sqrt_f32_e64 v220, |v220|
	v_sqrt_f32_e64 v221, |v221|
	v_mov_b32_dpp v166, v216 quad_perm:[1,0,3,2] row_mask:0xf bank_mask:0xf bound_ctrl:1
	v_mov_b32_dpp v167, v217 quad_perm:[1,0,3,2] row_mask:0xf bank_mask:0xf bound_ctrl:1
	v_pk_mul_f32 v[218:219], v[218:219], v[6:7]
	v_pk_mul_f32 v[220:221], v[220:221], v[8:9]
	v_perm_b32 v236, v166, v216, v125
	v_perm_b32 v237, v167, v217, v125
	global_store_dword v126, v236, s[16:17] offset:32
	global_store_dword v127, v237, s[16:17] offset:32
	v_pk_mul_f32 v[218:219], v[218:219], v[148:149]
	v_pk_mul_f32 v[220:221], v[220:221], v[150:151]
	v_pk_add_f32 v[2:3], v[2:3], v[4:5]
	v_cvt_pk_bf16_f32 v6, v218, v219
	v_cvt_pk_bf16_f32 v7, v220, v221
	v_add_f32_e32 v159, v2, v3
	v_lshlrev_b32_e32 v218, 16, v6
	v_mov_b32_dpp v166, v6 quad_perm:[1,0,3,2] row_mask:0xf bank_mask:0xf bound_ctrl:1
	v_and_b32_e32 v219, s21, v6
	v_mov_b32_dpp v167, v7 quad_perm:[1,0,3,2] row_mask:0xf bank_mask:0xf bound_ctrl:1
	v_lshlrev_b32_e32 v220, 16, v7
	v_and_b32_e32 v221, s21, v7
	v_perm_b32 v238, v166, v6, v125
	v_perm_b32 v239, v167, v7, v125
	global_store_dword v126, v238, s[18:19] offset:32
	global_store_dword v127, v239, s[18:19] offset:32
	v_fma_f32 v244, v218, v223, v219
	v_fma_f32 v245, v221, v224, v220
	v_fma_f32 v244, v244, v224, v220
	v_fma_f32 v245, v245, v223, v219
	v_fma_f32 v244, v244, v225, v221
	v_fma_f32 v245, v245, v222, v218
	ds_bpermute_b32 v240, v129, v159
	v_cndmask_b32_e64 v176, v245, v244, s[30:31]
	v_exp_f32_e32 v242, v159
	ds_bpermute_b32 v241, v129, v176
	s_waitcnt lgkmcnt(2)
	v_exp_f32_e32 v213, v210
	v_fma_f32 v215, v211, v212, v175
	v_add_f32_e32 v158, v158, v210
	v_fma_f32 v214, v175, v213, v211
	v_cndmask_b32_e64 v175, v215, v214, s[38:39]
	s_waitcnt lgkmcnt(0)
	v_exp_f32_e32 v243, v240
	v_fma_f32 v245, v241, v242, v176
	v_add_f32_e32 v159, v159, v240
	v_fma_f32 v244, v176, v243, v241
	v_cndmask_b32_e64 v176, v245, v244, s[40:41]
	ds_bpermute_b32 v240, v130, v159
	v_exp_f32_e32 v242, v159
	ds_bpermute_b32 v241, v130, v176
	s_waitcnt lgkmcnt(0)
	v_exp_f32_e32 v243, v240
	v_fma_f32 v245, v241, v242, v176
	v_add_f32_e32 v159, v159, v240
	v_fma_f32 v244, v176, v243, v241
	v_cndmask_b32_e64 v176, v245, v244, s[38:39]
	v_add_f32_e32 v178, v152, v153
	v_add_f32_e32 v179, v154, v155
	v_add_f32_e32 v180, v156, v157
	v_add_f32_e32 v181, v158, v159
	v_add_f32_e32 v178, v178, v179
	v_add_f32_e32 v180, v180, v181
	v_exp_f32_e32 v178, v178
	v_exp_f32_e32 v180, v180
	s_cmp_lg_u32 s10, 0
	s_cbranch_scc1 .Lrgx_bwd_np1
	v_exp_f32_e32 v184, v153
	v_exp_f32_e32 v185, v154
	v_exp_f32_e32 v186, v155
	v_exp_f32_e32 v222, v157
	v_exp_f32_e32 v223, v158
	v_exp_f32_e32 v224, v159
	v_fma_f32 v214, v169, v184, v170
	v_fma_f32 v215, v173, v222, v174
	v_fma_f32 v214, v214, v185, v171
	v_fma_f32 v215, v215, v223, v175
	v_fma_f32 v214, v214, v186, v172
	v_fma_f32 v215, v215, v224, v176
	s_branch .Lrgx_st_np1

; __device__ __forceinline__ float fexp2_(float x) { return __builtin_amdgcn_exp2f(x); }
; __device__ __forceinline__ void p_rg_fused(const Frame& F0, const bf16* URAW, int L, const float* cw, const float* cbias, const bf16* Wg, const float* ba, const float* bx, const float* spt,
;                                            bf16* LA, bf16* INP, float* HEND, float* PROD) {
;     ...
;                 if (g == 0) {
; #pragma unroll
;                     for (int ch = 0; ch < 2; ++ch) { const size_t o = ((size_t)(run * 2 + ch) * 2 + d) * D + c; HEND[o] = Hc[ch]; PROD[o] = fexp2_(Lc[ch]); } }
.Lrgx_st_np1:
	s_lshl_b32 s22, s10, 13
	s_lshl_b64 s[0:1], s[24:25], 2
	s_add_u32 s0, s0, s22
	s_addc_u32 s1, s1, 0
	s_lshl_b64 s[16:17], s[26:27], 2
	s_add_u32 s16, s16, s22
	s_addc_u32 s17, s17, 0
	s_add_u32 s18, s8, s0
	s_addc_u32 s19, s9, s1
	s_add_u32 s0, s6, s0
	s_addc_u32 s1, s7, s1
	s_add_u32 s22, s8, s16
	s_addc_u32 s23, s9, s17
	s_add_u32 s16, s6, s16
	s_addc_u32 s17, s7, s17
	s_mov_b64 vcc, exec
	s_and_b64 exec, exec, s[42:43]
	global_store_dword v128, v214, s[18:19] offset:64
	global_store_dword v128, v178, s[0:1] offset:64
	global_store_dword v128, v215, s[22:23] offset:64
	global_store_dword v128, v180, s[16:17] offset:64
	s_mov_b64 s[16:17], vcc
	s_branch .LBB0_855
